# BAR steps: row-sum adds of the first two P.V slots issued before the first P.V MFMA (LDS latency cover)
# baseline (speedup 1.0000x reference)
.LBB0_641:
	s_add_i32 s24, s23, -7
	s_lshl_b32 s92, s24, 13
	s_add_u32 vcc_lo, s100, s92
	s_addc_u32 vcc_hi, s101, 0
	global_load_dwordx4 v[52:55], v248, vcc
	s_add_i32 s24, s23, -8
	s_lshl_b32 s92, s24, 7
	s_add_u32 vcc_lo, s98, s92
	s_addc_u32 vcc_hi, s99, 0
	global_load_dwordx4 v[56:59], v249, vcc
	s_mul_i32 s26, s25, 0x2400
	s_add_i32 s24, s23, -7
	s_add_i32 s27, s26, 0xffffdc00
	s_cmp_lg_u32 s25, 0
	s_cselect_b32 s27, s27, 0x9000
	v_add_u32_e32 v1, s27, v163
	ds_read_b128 v[60:63], v1 offset:36864
	ds_read_b128 v[114:117], v1 offset:36896
	ds_read_b128 v[118:121], v1 offset:41472
	ds_read_b128 v[134:137], v1 offset:41504
	ds_read_b128 v[146:149], v1 offset:36928
	ds_read_b128 v[150:153], v1 offset:36960
	ds_read_b128 v[196:199], v1 offset:41536
	ds_read_b128 v[200:203], v1 offset:41568
	s_setprio 3
	v_cvt_pk_bf16_f32 v204, v102, v103
	v_cvt_pk_bf16_f32 v205, v104, v105
	v_cvt_pk_bf16_f32 v206, v98, v99
	v_cvt_pk_bf16_f32 v207, v100, v101
	s_waitcnt lgkmcnt(7)
	s_nop 0
	v_mfma_f32_32x32x16_bf16 v[18:33], v[60:63], v[204:207], v[18:33]
	v_add_f32_e32 v1, v102, v103
	v_add_f32_e32 v1, v1, v104
	v_add_f32_e32 v1, v1, v105
	s_waitcnt lgkmcnt(5)
	v_mfma_f32_32x32x16_bf16 v[2:17], v[118:121], v[204:207], v[2:17]
	v_cvt_pk_bf16_f32 v60, v194, v187
	v_cvt_pk_bf16_f32 v61, v186, v185
	v_cvt_pk_bf16_f32 v62, v133, v132
	v_cvt_pk_bf16_f32 v63, v131, v130
	v_add_f32_e32 v1, v1, v98
	v_add_f32_e32 v1, v1, v99
	v_add_f32_e32 v1, v1, v100
	v_add_f32_e32 v1, v1, v101
	s_nop 0
	v_mfma_f32_32x32x16_bf16 v[18:33], v[114:117], v[60:63], v[18:33]
	v_add_f32_e32 v1, v1, v194
	v_add_f32_e32 v1, v1, v187
	v_add_f32_e32 v1, v1, v186
	v_add_f32_e32 v1, v1, v185
	s_waitcnt lgkmcnt(4)
	v_mfma_f32_32x32x16_bf16 v[2:17], v[134:137], v[60:63], v[2:17]
	v_cvt_pk_bf16_f32 v98, v129, v128
	v_cvt_pk_bf16_f32 v99, v127, v126
	v_cvt_pk_bf16_f32 v100, v125, v124
	v_cvt_pk_bf16_f32 v101, v123, v122
	v_add_f32_e32 v1, v1, v133
	v_add_f32_e32 v1, v1, v132
	v_add_f32_e32 v1, v1, v131
	v_add_f32_e32 v1, v1, v130
	s_waitcnt lgkmcnt(3)
	v_mfma_f32_32x32x16_bf16 v[18:33], v[146:149], v[98:101], v[18:33]
	v_add_f32_e32 v1, v1, v129
	v_add_f32_e32 v1, v1, v128
	v_add_f32_e32 v1, v1, v127
	v_add_f32_e32 v1, v1, v126
	s_waitcnt lgkmcnt(1)
	v_mfma_f32_32x32x16_bf16 v[2:17], v[196:199], v[98:101], v[2:17]
	v_cvt_pk_bf16_f32 v60, v109, v108
	v_cvt_pk_bf16_f32 v61, v107, v106
	v_cvt_pk_bf16_f32 v62, v113, v112
	v_cvt_pk_bf16_f32 v63, v111, v110
	v_add_f32_e32 v1, v1, v125
	v_add_f32_e32 v1, v1, v124
	v_add_f32_e32 v1, v1, v123
	v_add_f32_e32 v1, v1, v122
	s_nop 0
	v_mfma_f32_32x32x16_bf16 v[18:33], v[150:153], v[60:63], v[18:33]
	v_add_f32_e32 v1, v1, v109
	v_add_f32_e32 v1, v1, v108
	v_add_f32_e32 v1, v1, v107
	v_add_f32_e32 v1, v1, v106
	s_waitcnt lgkmcnt(0)
	v_mfma_f32_32x32x16_bf16 v[2:17], v[200:203], v[60:63], v[2:17]
	v_add_f32_e32 v1, v1, v113
	v_add_f32_e32 v1, v1, v112
	v_add_f32_e32 v1, v1, v111
	v_add_f32_e32 v1, v1, v110
	s_setprio 2
	s_waitcnt lgkmcnt(0)
	s_barrier
	ds_read_b128 v[240:243], v165 offset:18432
	ds_read_b128 v[244:247], v165 offset:23040
	ds_read_b128 v[130:133], v165 offset:18464
	ds_read_b128 v[146:149], v165 offset:23072
	v_exp_f32_e32 v185, v82
	v_exp_f32_e32 v186, v83
	v_exp_f32_e32 v187, v84
	v_exp_f32_e32 v194, v85
	v_exp_f32_e32 v195, v86
	v_exp_f32_e32 v196, v87
	v_exp_f32_e32 v197, v88
	v_exp_f32_e32 v198, v89
	s_waitcnt lgkmcnt(2)
	v_mfma_f32_32x32x16_bf16 v[114:129], v[240:243], v[158:161], v[34:49]
	s_waitcnt lgkmcnt(1)
	v_mfma_f32_32x32x16_bf16 v[98:113], v[244:247], v[158:161], v[34:49]
	v_exp_f32_e32 v199, v90
	v_exp_f32_e32 v200, v91
	v_exp_f32_e32 v201, v92
	v_exp_f32_e32 v202, v93
	v_exp_f32_e32 v134, v94
	v_exp_f32_e32 v135, v95
	v_exp_f32_e32 v136, v96
	v_exp_f32_e32 v137, v97
	v_mfma_f32_32x32x16_bf16 v[114:129], v[130:133], v[154:157], v[114:129]
	v_exp_f32_e32 v96, v66
	v_exp_f32_e32 v97, v67
	v_exp_f32_e32 v203, v68
	v_exp_f32_e32 v204, v69
	v_exp_f32_e32 v130, v70
	v_exp_f32_e32 v131, v71
	v_exp_f32_e32 v132, v72
	v_exp_f32_e32 v133, v73
	s_waitcnt lgkmcnt(0)
	v_mfma_f32_32x32x16_bf16 v[98:113], v[146:149], v[154:157], v[98:113]
	v_exp_f32_e32 v205, v74
	v_exp_f32_e32 v206, v75
	v_exp_f32_e32 v207, v76
	v_exp_f32_e32 v208, v77
	v_exp_f32_e32 v209, v78
	v_exp_f32_e32 v210, v79
	v_exp_f32_e32 v211, v80
	v_exp_f32_e32 v212, v81
	v_add_u32_e32 v88, s26, v163
	ds_read_b128 v[240:243], v165 offset:27648
	ds_read_b128 v[244:247], v165 offset:32256
	ds_read_b128 v[60:63], v88 offset:41472
	ds_read_b128 v[64:67], v88 offset:36864
	ds_read_b128 v[68:71], v88 offset:36896
	ds_read_b128 v[72:75], v88 offset:41504
	ds_read_b128 v[76:79], v88 offset:36928
	ds_read_b128 v[80:83], v88 offset:41536
	ds_read_b128 v[84:87], v88 offset:36960
	ds_read_b128 v[88:91], v88 offset:41568
	s_cmp_gt_i32 s25, 2
	s_cselect_b32 s27, -3, 2
	s_add_i32 s27, s27, s25
	s_add_i32 s26, s23, -6
	s_mulk_i32 s27, 0x2400
	s_min_u32 s26, s26, s13
	v_add_u32_e32 v51, s27, v182
	s_min_u32 s24, s24, s13
	s_lshl_b32 s92, s26, 13
	s_waitcnt vmcnt(3)
	ds_write_b128 v182, v[138:141]
	s_waitcnt vmcnt(2)
	ds_write_b128 v51, v[142:145] offset:36864
	v_add_f32_e32 v1, v50, v1
	s_add_u32 vcc_lo, s100, s92
	s_addc_u32 vcc_hi, s101, 0
	global_load_dwordx4 v[146:149], v248, vcc
	s_lshl_b32 s92, s24, 7
	s_add_u32 vcc_lo, s98, s92
	s_addc_u32 vcc_hi, s99, 0
	global_load_dwordx4 v[150:153], v249, vcc
	s_add_i32 s27, s25, 1
	s_setprio 1
	v_cvt_pk_bf16_f32 v92, v185, v186
	v_cvt_pk_bf16_f32 v93, v187, v194
	v_cvt_pk_bf16_f32 v94, v195, v196
	v_cvt_pk_bf16_f32 v95, v197, v198
	s_waitcnt lgkmcnt(8)
	s_nop 0
	v_mfma_f32_32x32x16_bf16 v[18:33], v[64:67], v[92:95], v[18:33]
	v_add_f32_e32 v213, v185, v186
	v_add_f32_e32 v213, v213, v187
	v_add_f32_e32 v213, v213, v194
	s_nop 0
	v_mfma_f32_32x32x16_bf16 v[2:17], v[60:63], v[92:95], v[2:17]
	v_cvt_pk_bf16_f32 v64, v199, v200
	v_cvt_pk_bf16_f32 v65, v201, v202
	v_cvt_pk_bf16_f32 v66, v134, v135
	v_cvt_pk_bf16_f32 v67, v136, v137
	v_add_f32_e32 v213, v213, v195
	v_add_f32_e32 v213, v213, v196
	v_add_f32_e32 v213, v213, v197
	v_add_f32_e32 v213, v213, v198
	s_waitcnt lgkmcnt(7)
	v_mfma_f32_32x32x16_bf16 v[18:33], v[68:71], v[64:67], v[18:33]
	v_add_f32_e32 v213, v213, v199
	v_add_f32_e32 v213, v213, v200
	v_add_f32_e32 v213, v213, v201
	v_add_f32_e32 v213, v213, v202
	s_waitcnt lgkmcnt(6)
	v_mfma_f32_32x32x16_bf16 v[2:17], v[72:75], v[64:67], v[2:17]
	v_cvt_pk_bf16_f32 v60, v96, v97
	v_cvt_pk_bf16_f32 v61, v203, v204
	v_cvt_pk_bf16_f32 v62, v130, v131
	v_cvt_pk_bf16_f32 v63, v132, v133
	v_add_f32_e32 v213, v213, v134
	v_add_f32_e32 v213, v213, v135
	v_add_f32_e32 v213, v213, v136
	v_add_f32_e32 v213, v213, v137
	s_waitcnt lgkmcnt(5)
	v_mfma_f32_32x32x16_bf16 v[18:33], v[76:79], v[60:63], v[18:33]
	v_add_f32_e32 v213, v213, v96
	v_add_f32_e32 v213, v213, v97
	v_add_f32_e32 v213, v213, v203
	v_add_f32_e32 v213, v213, v204
	s_waitcnt lgkmcnt(4)
	v_mfma_f32_32x32x16_bf16 v[2:17], v[80:83], v[60:63], v[2:17]
	v_cvt_pk_bf16_f32 v64, v205, v206
	v_cvt_pk_bf16_f32 v65, v207, v208
	v_cvt_pk_bf16_f32 v66, v209, v210
	v_cvt_pk_bf16_f32 v67, v211, v212
	v_add_f32_e32 v213, v213, v130
	v_add_f32_e32 v213, v213, v131
	v_add_f32_e32 v213, v213, v132
	v_add_f32_e32 v213, v213, v133
	s_waitcnt lgkmcnt(3)
	v_mfma_f32_32x32x16_bf16 v[18:33], v[84:87], v[64:67], v[18:33]
	v_add_f32_e32 v213, v213, v205
	v_add_f32_e32 v213, v213, v206
	v_add_f32_e32 v213, v213, v207
	v_add_f32_e32 v213, v213, v208
	s_waitcnt lgkmcnt(2)
	v_mfma_f32_32x32x16_bf16 v[2:17], v[88:91], v[64:67], v[2:17]
	v_add_f32_e32 v213, v213, v209
	v_add_f32_e32 v213, v213, v210
	v_add_f32_e32 v213, v213, v211
	v_add_f32_e32 v213, v213, v212
	s_setprio 0
	ds_read_b128 v[64:67], v165 offset:27680
	ds_read_b128 v[72:75], v165 offset:32288
	s_cmp_lg_u32 s25, 4
	s_cselect_b32 s24, s27, 0
	s_waitcnt lgkmcnt(2)
	v_mfma_f32_32x32x16_bf16 v[130:145], v[240:243], v[158:161], v[34:49]
	v_exp_f32_e32 v185, v114
	v_exp_f32_e32 v186, v115
	v_exp_f32_e32 v187, v116
	v_exp_f32_e32 v194, v117
	v_exp_f32_e32 v195, v118
	v_exp_f32_e32 v196, v119
	v_exp_f32_e32 v197, v120
	v_exp_f32_e32 v198, v121
	s_waitcnt lgkmcnt(1)
	v_mfma_f32_32x32x16_bf16 v[82:97], v[244:247], v[158:161], v[34:49]
	v_exp_f32_e32 v199, v122
	v_exp_f32_e32 v200, v123
	v_exp_f32_e32 v201, v124
	v_exp_f32_e32 v202, v125
	v_exp_f32_e32 v122, v126
	v_exp_f32_e32 v123, v127
	v_exp_f32_e32 v124, v128
	v_exp_f32_e32 v125, v129
	v_mfma_f32_32x32x16_bf16 v[130:145], v[64:67], v[154:157], v[130:145]
	v_exp_f32_e32 v126, v98
	v_exp_f32_e32 v127, v99
	v_exp_f32_e32 v128, v100
	v_exp_f32_e32 v129, v101
	v_exp_f32_e32 v203, v102
	v_exp_f32_e32 v204, v103
	v_exp_f32_e32 v205, v104
	v_exp_f32_e32 v206, v105
	s_waitcnt lgkmcnt(0)
	v_mfma_f32_32x32x16_bf16 v[82:97], v[72:75], v[154:157], v[82:97]
	v_exp_f32_e32 v102, v106
	v_exp_f32_e32 v103, v107
	v_exp_f32_e32 v104, v108
	v_exp_f32_e32 v105, v109
	v_exp_f32_e32 v106, v110
	v_exp_f32_e32 v107, v111
	v_exp_f32_e32 v108, v112
	v_exp_f32_e32 v109, v113
	s_cmp_gt_i32 s24, 2
	s_cselect_b32 s25, -3, 2
	s_add_i32 s25, s25, s24
	s_mulk_i32 s25, 0x2400
	v_add_u32_e32 v50, s25, v182
	s_add_i32 s25, s24, 1
	s_cmp_lg_u32 s24, 4
	s_cselect_b32 s24, s25, 0
	s_add_i32 s25, s23, -5
	s_min_u32 s25, s25, s13
	s_lshl_b32 s92, s25, 13
	s_waitcnt vmcnt(3)
	ds_write_b128 v182, v[52:55] offset:9216
	s_waitcnt vmcnt(2)
	ds_write_b128 v50, v[56:59] offset:36864
	s_add_u32 vcc_lo, s100, s92
	s_addc_u32 vcc_hi, s101, 0
	global_load_dwordx4 v[118:121], v248, vcc
	s_lshl_b32 s92, s26, 7
	s_add_u32 vcc_lo, s98, s92
	s_addc_u32 vcc_hi, s99, 0
	global_load_dwordx4 v[114:117], v249, vcc
	s_mul_i32 s26, s24, 0x2400
	s_add_i32 s27, s26, 0xffffdc00
	s_cmp_lg_u32 s24, 0
	s_cselect_b32 s27, s27, 0x9000
	v_add_u32_e32 v78, s27, v163
	ds_read_b128 v[50:53], v78 offset:36864
	ds_read_b128 v[54:57], v78 offset:36896
	ds_read_b128 v[58:61], v78 offset:41472
	ds_read_b128 v[62:65], v78 offset:41504
	ds_read_b128 v[66:69], v78 offset:36928
	ds_read_b128 v[70:73], v78 offset:36960
	ds_read_b128 v[74:77], v78 offset:41536
	ds_read_b128 v[78:81], v78 offset:41568
	s_setprio 3
	v_cvt_pk_bf16_f32 v98, v185, v186
	v_cvt_pk_bf16_f32 v99, v187, v194
	v_cvt_pk_bf16_f32 v100, v195, v196
	v_cvt_pk_bf16_f32 v101, v197, v198
	v_add_f32_e32 v110, v185, v186
	v_add_f32_e32 v110, v110, v187
	v_add_f32_e32 v110, v110, v194
	v_add_f32_e32 v110, v110, v195
	v_add_f32_e32 v110, v110, v196
	v_add_f32_e32 v110, v110, v197
	v_add_f32_e32 v110, v110, v198
	s_waitcnt lgkmcnt(7)
	s_nop 0
	v_mfma_f32_32x32x16_bf16 v[18:33], v[50:53], v[98:101], v[18:33]
	s_waitcnt lgkmcnt(5)
	v_mfma_f32_32x32x16_bf16 v[2:17], v[58:61], v[98:101], v[2:17]
	v_cvt_pk_bf16_f32 v50, v199, v200
	v_cvt_pk_bf16_f32 v51, v201, v202
	v_cvt_pk_bf16_f32 v52, v122, v123
	v_cvt_pk_bf16_f32 v53, v124, v125
	s_nop 0
	v_mfma_f32_32x32x16_bf16 v[18:33], v[54:57], v[50:53], v[18:33]
	v_add_f32_e32 v110, v110, v199
	v_add_f32_e32 v110, v110, v200
	v_add_f32_e32 v110, v110, v201
	v_add_f32_e32 v110, v110, v202
	s_waitcnt lgkmcnt(4)
	v_mfma_f32_32x32x16_bf16 v[2:17], v[62:65], v[50:53], v[2:17]
	v_cvt_pk_bf16_f32 v54, v126, v127
	v_cvt_pk_bf16_f32 v55, v128, v129
	v_cvt_pk_bf16_f32 v56, v203, v204
	v_cvt_pk_bf16_f32 v57, v205, v206
	v_add_f32_e32 v110, v110, v122
	v_add_f32_e32 v110, v110, v123
	v_add_f32_e32 v110, v110, v124
	v_add_f32_e32 v110, v110, v125
	s_waitcnt lgkmcnt(3)
	v_mfma_f32_32x32x16_bf16 v[18:33], v[66:69], v[54:57], v[18:33]
	v_add_f32_e32 v110, v110, v126
	v_add_f32_e32 v110, v110, v127
	v_add_f32_e32 v110, v110, v128
	v_add_f32_e32 v110, v110, v129
	s_waitcnt lgkmcnt(1)
	v_mfma_f32_32x32x16_bf16 v[2:17], v[74:77], v[54:57], v[2:17]
	v_cvt_pk_bf16_f32 v50, v102, v103
	v_cvt_pk_bf16_f32 v51, v104, v105
	v_cvt_pk_bf16_f32 v52, v106, v107
	v_cvt_pk_bf16_f32 v53, v108, v109
	v_add_f32_e32 v110, v110, v203
	v_add_f32_e32 v110, v110, v204
	v_add_f32_e32 v110, v110, v205
	v_add_f32_e32 v110, v110, v206
	s_nop 0
	v_mfma_f32_32x32x16_bf16 v[18:33], v[70:73], v[50:53], v[18:33]
	v_add_f32_e32 v110, v110, v102
	v_add_f32_e32 v110, v110, v103
	v_add_f32_e32 v110, v110, v104
	v_add_f32_e32 v110, v110, v105
	s_waitcnt lgkmcnt(0)
	v_mfma_f32_32x32x16_bf16 v[2:17], v[78:81], v[50:53], v[2:17]
	v_add_f32_e32 v110, v110, v106
	v_add_f32_e32 v110, v110, v107
	v_add_f32_e32 v110, v110, v108
	v_add_f32_e32 v110, v110, v109
	s_setprio 2
	s_waitcnt lgkmcnt(0)
	s_barrier
	ds_read_b128 v[240:243], v165
	ds_read_b128 v[244:247], v165 offset:4608
	ds_read_b128 v[102:105], v165 offset:32
	ds_read_b128 v[106:109], v165 offset:4640
	v_add_f32_e32 v1, v1, v213
	v_exp_f32_e32 v185, v130
	v_exp_f32_e32 v186, v131
	v_exp_f32_e32 v187, v132
	v_exp_f32_e32 v194, v133
	v_exp_f32_e32 v195, v134
	v_exp_f32_e32 v196, v135
	v_exp_f32_e32 v197, v136
	v_exp_f32_e32 v198, v137
	s_waitcnt lgkmcnt(2)
	v_mfma_f32_32x32x16_bf16 v[66:81], v[240:243], v[158:161], v[34:49]
	v_mfma_f32_32x32x16_bf16 v[50:65], v[244:247], v[158:161], v[34:49]
	v_exp_f32_e32 v134, v138
	v_exp_f32_e32 v135, v139
	v_exp_f32_e32 v136, v140
	v_exp_f32_e32 v137, v141
	v_exp_f32_e32 v138, v142
	v_exp_f32_e32 v139, v143
	v_exp_f32_e32 v140, v144
	v_exp_f32_e32 v141, v145
	s_waitcnt lgkmcnt(1)
	v_mfma_f32_32x32x16_bf16 v[66:81], v[102:105], v[154:157], v[66:81]
	v_exp_f32_e32 v142, v82
	v_exp_f32_e32 v143, v83
	v_exp_f32_e32 v144, v84
	v_exp_f32_e32 v145, v85
	v_exp_f32_e32 v199, v86
	v_exp_f32_e32 v200, v87
	v_exp_f32_e32 v201, v88
	v_exp_f32_e32 v202, v89
	s_waitcnt lgkmcnt(0)
	v_mfma_f32_32x32x16_bf16 v[50:65], v[106:109], v[154:157], v[50:65]
	v_exp_f32_e32 v203, v90
	v_exp_f32_e32 v204, v91
	v_exp_f32_e32 v205, v92
	v_exp_f32_e32 v206, v93
	v_exp_f32_e32 v207, v94
	v_exp_f32_e32 v208, v95
	v_exp_f32_e32 v209, v96
	v_exp_f32_e32 v210, v97
	v_add_f32_e32 v1, v1, v110
	v_add_u32_e32 v111, s26, v163
	ds_read_b128 v[240:243], v165 offset:9216
	ds_read_b128 v[244:247], v165 offset:13824
	ds_read_b128 v[82:85], v111 offset:41472
	ds_read_b128 v[86:89], v111 offset:36864
	ds_read_b128 v[90:93], v111 offset:36896
	ds_read_b128 v[94:97], v111 offset:41504
	ds_read_b128 v[98:101], v111 offset:36928
	ds_read_b128 v[102:105], v111 offset:41536
	ds_read_b128 v[106:109], v111 offset:36960
	ds_read_b128 v[110:113], v111 offset:41568
	s_cmp_gt_i32 s24, 2
	s_cselect_b32 s27, -3, 2
	s_add_i32 s27, s27, s24
	s_mulk_i32 s27, 0x2400
	v_add_u32_e32 v250, s27, v182
	s_mov_b32 s27, 0x18950000
	s_waitcnt vmcnt(3)
	ds_write_b128 v182, v[146:149] offset:18432
	s_waitcnt vmcnt(2)
	ds_write_b128 v250, v[150:153] offset:36864
	s_add_i32 s92, s23, -4
	s_lshl_b32 s92, s92, 13
	s_add_u32 vcc_lo, s100, s92
	s_addc_u32 vcc_hi, s101, 0
	global_load_dwordx4 v[126:129], v248, vcc
	s_lshl_b32 s92, s25, 7
	s_add_u32 vcc_lo, s98, s92
	s_addc_u32 vcc_hi, s99, 0
	global_load_dwordx4 v[122:125], v249, vcc
	s_add_i32 s26, s24, 1
	s_setprio 1
	v_cvt_pk_bf16_f32 v130, v185, v186
	v_cvt_pk_bf16_f32 v131, v187, v194
	v_cvt_pk_bf16_f32 v132, v195, v196
	v_cvt_pk_bf16_f32 v133, v197, v198
	s_waitcnt lgkmcnt(8)
	s_nop 0
	v_mfma_f32_32x32x16_bf16 v[18:33], v[86:89], v[130:133], v[18:33]
	v_add_f32_e32 v146, v185, v186
	v_add_f32_e32 v146, v146, v187
	v_add_f32_e32 v146, v146, v194
	s_nop 0
	v_mfma_f32_32x32x16_bf16 v[2:17], v[82:85], v[130:133], v[2:17]
	v_cvt_pk_bf16_f32 v86, v134, v135
	v_cvt_pk_bf16_f32 v87, v136, v137
	v_cvt_pk_bf16_f32 v88, v138, v139
	v_cvt_pk_bf16_f32 v89, v140, v141
	v_add_f32_e32 v146, v146, v195
	v_add_f32_e32 v146, v146, v196
	v_add_f32_e32 v146, v146, v197
	v_add_f32_e32 v146, v146, v198
	s_waitcnt lgkmcnt(7)
	v_mfma_f32_32x32x16_bf16 v[18:33], v[90:93], v[86:89], v[18:33]
	v_add_f32_e32 v146, v146, v134
	v_add_f32_e32 v146, v146, v135
	v_add_f32_e32 v146, v146, v136
	v_add_f32_e32 v146, v146, v137
	s_waitcnt lgkmcnt(6)
	v_mfma_f32_32x32x16_bf16 v[2:17], v[94:97], v[86:89], v[2:17]
	v_cvt_pk_bf16_f32 v82, v142, v143
	v_cvt_pk_bf16_f32 v83, v144, v145
	v_cvt_pk_bf16_f32 v84, v199, v200
	v_cvt_pk_bf16_f32 v85, v201, v202
	v_add_f32_e32 v146, v146, v138
	v_add_f32_e32 v146, v146, v139
	v_add_f32_e32 v146, v146, v140
	v_add_f32_e32 v146, v146, v141
	s_waitcnt lgkmcnt(5)
	v_mfma_f32_32x32x16_bf16 v[18:33], v[98:101], v[82:85], v[18:33]
	v_add_f32_e32 v146, v146, v142
	v_add_f32_e32 v146, v146, v143
	v_add_f32_e32 v146, v146, v144
	v_add_f32_e32 v146, v146, v145
	s_waitcnt lgkmcnt(4)
	v_mfma_f32_32x32x16_bf16 v[2:17], v[102:105], v[82:85], v[2:17]
	v_cvt_pk_bf16_f32 v86, v203, v204
	v_cvt_pk_bf16_f32 v87, v205, v206
	v_cvt_pk_bf16_f32 v88, v207, v208
	v_cvt_pk_bf16_f32 v89, v209, v210
	v_add_f32_e32 v146, v146, v199
	v_add_f32_e32 v146, v146, v200
	v_add_f32_e32 v146, v146, v201
	v_add_f32_e32 v146, v146, v202
	s_waitcnt lgkmcnt(3)
	v_mfma_f32_32x32x16_bf16 v[18:33], v[106:109], v[86:89], v[18:33]
	v_add_f32_e32 v146, v146, v203
	v_add_f32_e32 v146, v146, v204
	v_add_f32_e32 v146, v146, v205
	v_add_f32_e32 v146, v146, v206
	s_waitcnt lgkmcnt(2)
	v_mfma_f32_32x32x16_bf16 v[2:17], v[110:113], v[86:89], v[2:17]
	v_add_f32_e32 v146, v146, v207
	v_add_f32_e32 v146, v146, v208
	v_add_f32_e32 v146, v146, v209
	v_add_f32_e32 v146, v146, v210
	s_setprio 0
	ds_read_b128 v[130:133], v165 offset:9248
	ds_read_b128 v[138:141], v165 offset:13856
	s_cmp_lg_u32 s24, 4
	s_cselect_b32 s24, s26, 0
	s_waitcnt lgkmcnt(2)
	v_mfma_f32_32x32x16_bf16 v[98:113], v[240:243], v[158:161], v[34:49]
	v_exp_f32_e32 v142, v66
	v_exp_f32_e32 v143, v67
	v_exp_f32_e32 v144, v68
	v_exp_f32_e32 v145, v69
	v_exp_f32_e32 v147, v70
	v_exp_f32_e32 v148, v71
	v_exp_f32_e32 v149, v72
	v_exp_f32_e32 v150, v73
	s_waitcnt lgkmcnt(1)
	v_mfma_f32_32x32x16_bf16 v[82:97], v[244:247], v[158:161], v[34:49]
	v_exp_f32_e32 v151, v74
	v_exp_f32_e32 v152, v75
	v_exp_f32_e32 v153, v76
	v_exp_f32_e32 v178, v77
	v_exp_f32_e32 v134, v78
	v_exp_f32_e32 v135, v79
	v_exp_f32_e32 v136, v80
	v_exp_f32_e32 v137, v81
	v_mfma_f32_32x32x16_bf16 v[98:113], v[130:133], v[154:157], v[98:113]
	v_exp_f32_e32 v179, v50
	v_exp_f32_e32 v185, v51
	v_exp_f32_e32 v186, v52
	v_exp_f32_e32 v187, v53
	v_exp_f32_e32 v194, v54
	v_exp_f32_e32 v195, v55
	v_exp_f32_e32 v196, v56
	v_exp_f32_e32 v197, v57
	s_waitcnt lgkmcnt(0)
	v_mfma_f32_32x32x16_bf16 v[82:97], v[138:141], v[154:157], v[82:97]
	v_exp_f32_e32 v198, v58
	v_exp_f32_e32 v199, v59
	v_exp_f32_e32 v200, v60
	v_exp_f32_e32 v201, v61
	v_exp_f32_e32 v138, v62
	v_exp_f32_e32 v139, v63
	v_exp_f32_e32 v140, v64
	v_exp_f32_e32 v141, v65
	s_cmp_gt_i32 s24, 2
	s_cselect_b32 s25, -3, 2
	s_add_i32 s25, s25, s24
	s_mulk_i32 s25, 0x2400
	v_add_u32_e32 v50, s25, v182
	s_add_i32 s25, s24, 1
	s_cmp_lg_u32 s24, 4
	s_cselect_b32 s25, s25, 0
	s_add_i32 s24, s23, -3
	s_min_u32 s26, s24, s13
	s_lshl_b32 s92, s26, 13
	s_waitcnt vmcnt(3)
	ds_write_b128 v182, v[118:121] offset:27648
	s_waitcnt vmcnt(2)
	ds_write_b128 v50, v[114:117] offset:36864
	s_add_u32 vcc_lo, s100, s92
	s_addc_u32 vcc_hi, s101, 0
	global_load_dwordx4 v[118:121], v248, vcc
	s_add_i32 s92, s23, -4
	s_lshl_b32 s92, s92, 7
	s_add_u32 vcc_lo, s98, s92
	s_addc_u32 vcc_hi, s99, 0
	global_load_dwordx4 v[114:117], v249, vcc
	s_mul_i32 s27, s25, 0x2400
	s_add_i32 s28, s27, 0xffffdc00
	s_cmp_lg_u32 s25, 0
	s_cselect_b32 s28, s28, 0x9000
	v_add_u32_e32 v78, s28, v163
	ds_read_b128 v[50:53], v78 offset:36864
	ds_read_b128 v[54:57], v78 offset:36896
	ds_read_b128 v[58:61], v78 offset:41472
	ds_read_b128 v[62:65], v78 offset:41504
	ds_read_b128 v[66:69], v78 offset:36928
	ds_read_b128 v[70:73], v78 offset:36960
	ds_read_b128 v[74:77], v78 offset:41536
	ds_read_b128 v[78:81], v78 offset:41568
	s_setprio 3
	v_cvt_pk_bf16_f32 v130, v142, v143
	v_cvt_pk_bf16_f32 v131, v144, v145
	v_cvt_pk_bf16_f32 v132, v147, v148
	v_cvt_pk_bf16_f32 v133, v149, v150
	v_add_f32_e32 v176, v142, v143
	v_add_f32_e32 v176, v176, v144
	v_add_f32_e32 v176, v176, v145
	v_add_f32_e32 v176, v176, v147
	v_add_f32_e32 v176, v176, v148
	v_add_f32_e32 v176, v176, v149
	v_add_f32_e32 v176, v176, v150
	s_waitcnt lgkmcnt(7)
	s_nop 0
	v_mfma_f32_32x32x16_bf16 v[18:33], v[50:53], v[130:133], v[18:33]
	s_waitcnt lgkmcnt(5)
	v_mfma_f32_32x32x16_bf16 v[2:17], v[58:61], v[130:133], v[2:17]
	v_cvt_pk_bf16_f32 v50, v151, v152
	v_cvt_pk_bf16_f32 v51, v153, v178
	v_cvt_pk_bf16_f32 v52, v134, v135
	v_cvt_pk_bf16_f32 v53, v136, v137
	s_nop 0
	v_mfma_f32_32x32x16_bf16 v[18:33], v[54:57], v[50:53], v[18:33]
	v_add_f32_e32 v176, v176, v151
	v_add_f32_e32 v176, v176, v152
	v_add_f32_e32 v176, v176, v153
	v_add_f32_e32 v176, v176, v178
	s_waitcnt lgkmcnt(4)
	v_mfma_f32_32x32x16_bf16 v[2:17], v[62:65], v[50:53], v[2:17]
	v_cvt_pk_bf16_f32 v54, v179, v185
	v_cvt_pk_bf16_f32 v55, v186, v187
	v_cvt_pk_bf16_f32 v56, v194, v195
	v_cvt_pk_bf16_f32 v57, v196, v197
	v_add_f32_e32 v176, v176, v134
	v_add_f32_e32 v176, v176, v135
	v_add_f32_e32 v176, v176, v136
	v_add_f32_e32 v176, v176, v137
	s_waitcnt lgkmcnt(3)
	v_mfma_f32_32x32x16_bf16 v[18:33], v[66:69], v[54:57], v[18:33]
	v_add_f32_e32 v176, v176, v179
	v_add_f32_e32 v176, v176, v185
	v_add_f32_e32 v176, v176, v186
	v_add_f32_e32 v176, v176, v187
	s_waitcnt lgkmcnt(1)
	v_mfma_f32_32x32x16_bf16 v[2:17], v[74:77], v[54:57], v[2:17]
	v_cvt_pk_bf16_f32 v50, v198, v199
	v_cvt_pk_bf16_f32 v51, v200, v201
	v_cvt_pk_bf16_f32 v52, v138, v139
	v_cvt_pk_bf16_f32 v53, v140, v141
	v_add_f32_e32 v176, v176, v194
	v_add_f32_e32 v176, v176, v195
	v_add_f32_e32 v176, v176, v196
	v_add_f32_e32 v176, v176, v197
	s_nop 0
	v_mfma_f32_32x32x16_bf16 v[18:33], v[70:73], v[50:53], v[18:33]
	v_add_f32_e32 v176, v176, v198
	v_add_f32_e32 v176, v176, v199
	v_add_f32_e32 v176, v176, v200
	v_add_f32_e32 v176, v176, v201
	s_waitcnt lgkmcnt(0)
	v_mfma_f32_32x32x16_bf16 v[2:17], v[78:81], v[50:53], v[2:17]
	v_add_f32_e32 v176, v176, v138
	v_add_f32_e32 v176, v176, v139
	v_add_f32_e32 v176, v176, v140
	v_add_f32_e32 v176, v176, v141
	s_setprio 2
	s_waitcnt lgkmcnt(0)
	s_barrier
	ds_read_b128 v[240:243], v165 offset:18432
	ds_read_b128 v[244:247], v165 offset:23040
	ds_read_b128 v[134:137], v165 offset:18464
	ds_read_b128 v[138:141], v165 offset:23072
	v_add_f32_e32 v1, v1, v146
	v_exp_f32_e32 v142, v98
	v_exp_f32_e32 v143, v99
	v_exp_f32_e32 v144, v100
	v_exp_f32_e32 v145, v101
	v_exp_f32_e32 v146, v102
	v_exp_f32_e32 v147, v103
	v_exp_f32_e32 v148, v104
	v_exp_f32_e32 v149, v105
	s_waitcnt lgkmcnt(2)
	v_mfma_f32_32x32x16_bf16 v[66:81], v[240:243], v[158:161], v[34:49]
	v_mfma_f32_32x32x16_bf16 v[50:65], v[244:247], v[158:161], v[34:49]
	v_exp_f32_e32 v150, v106
	v_exp_f32_e32 v151, v107
	v_exp_f32_e32 v152, v108
	v_exp_f32_e32 v153, v109
	v_exp_f32_e32 v177, v110
	v_exp_f32_e32 v178, v111
	v_exp_f32_e32 v179, v112
	v_exp_f32_e32 v185, v113
	s_waitcnt lgkmcnt(1)
	v_mfma_f32_32x32x16_bf16 v[66:81], v[134:137], v[154:157], v[66:81]
	v_exp_f32_e32 v186, v82
	v_exp_f32_e32 v187, v83
	v_exp_f32_e32 v194, v84
	v_exp_f32_e32 v195, v85
	v_exp_f32_e32 v134, v86
	v_exp_f32_e32 v135, v87
	v_exp_f32_e32 v136, v88
	v_exp_f32_e32 v137, v89
	s_waitcnt lgkmcnt(0)
	v_mfma_f32_32x32x16_bf16 v[50:65], v[138:141], v[154:157], v[50:65]
	v_exp_f32_e32 v196, v90
	v_exp_f32_e32 v197, v91
	v_exp_f32_e32 v198, v92
	v_exp_f32_e32 v199, v93
	v_exp_f32_e32 v138, v94
	v_exp_f32_e32 v139, v95
	v_exp_f32_e32 v140, v96
	v_exp_f32_e32 v141, v97
	s_cmp_gt_i32 s25, 2
	s_cselect_b32 s28, -3, 2
	s_waitcnt vmcnt(3)
	ds_write_b128 v182, v[126:129]
	s_add_i32 s28, s28, s25
	v_add_u32_e32 v126, s27, v163
	s_add_i32 s27, s23, -2
	s_mulk_i32 s28, 0x2400
	s_min_u32 s27, s27, s13
	v_add_u32_e32 v82, s28, v182
	s_lshl_b32 s92, s27, 13
	s_waitcnt vmcnt(2)
	ds_write_b128 v82, v[122:125] offset:36864
	ds_read_b128 v[240:243], v165 offset:27648
	ds_read_b128 v[244:247], v165 offset:32256
	ds_read_b128 v[82:85], v126 offset:41472
	ds_read_b128 v[86:89], v126 offset:36864
	ds_read_b128 v[90:93], v126 offset:36896
	ds_read_b128 v[94:97], v126 offset:41504
	ds_read_b128 v[106:109], v126 offset:36928
	ds_read_b128 v[110:113], v126 offset:41536
	ds_read_b128 v[122:125], v126 offset:36960
	ds_read_b128 v[126:129], v126 offset:41568
	s_add_u32 vcc_lo, s100, s92
	s_addc_u32 vcc_hi, s101, 0
	global_load_dwordx4 v[98:101], v248, vcc
	s_lshl_b32 s92, s26, 7
	s_add_u32 vcc_lo, s98, s92
	s_addc_u32 vcc_hi, s99, 0
	global_load_dwordx4 v[102:105], v249, vcc
	v_add_f32_e32 v1, v1, v176
	s_add_i32 s28, s25, 1
	s_setprio 1
	v_cvt_pk_bf16_f32 v130, v142, v143
	v_cvt_pk_bf16_f32 v131, v144, v145
	v_cvt_pk_bf16_f32 v132, v146, v147
	v_cvt_pk_bf16_f32 v133, v148, v149
	s_waitcnt lgkmcnt(6)
	s_nop 0
	v_mfma_f32_32x32x16_bf16 v[18:33], v[86:89], v[130:133], v[18:33]
	v_add_f32_e32 v176, v142, v143
	v_add_f32_e32 v176, v176, v144
	v_add_f32_e32 v176, v176, v145
	s_nop 0
	v_mfma_f32_32x32x16_bf16 v[2:17], v[82:85], v[130:133], v[2:17]
	v_cvt_pk_bf16_f32 v86, v150, v151
	v_cvt_pk_bf16_f32 v87, v152, v153
	v_cvt_pk_bf16_f32 v88, v177, v178
	v_cvt_pk_bf16_f32 v89, v179, v185
	v_add_f32_e32 v176, v176, v146
	v_add_f32_e32 v176, v176, v147
	v_add_f32_e32 v176, v176, v148
	v_add_f32_e32 v176, v176, v149
	s_waitcnt lgkmcnt(5)
	v_mfma_f32_32x32x16_bf16 v[18:33], v[90:93], v[86:89], v[18:33]
	v_add_f32_e32 v176, v176, v150
	v_add_f32_e32 v176, v176, v151
	v_add_f32_e32 v176, v176, v152
	v_add_f32_e32 v176, v176, v153
	s_waitcnt lgkmcnt(4)
	v_mfma_f32_32x32x16_bf16 v[2:17], v[94:97], v[86:89], v[2:17]
	v_cvt_pk_bf16_f32 v82, v186, v187
	v_cvt_pk_bf16_f32 v83, v194, v195
	v_cvt_pk_bf16_f32 v84, v134, v135
	v_cvt_pk_bf16_f32 v85, v136, v137
	v_add_f32_e32 v176, v176, v177
	v_add_f32_e32 v176, v176, v178
	v_add_f32_e32 v176, v176, v179
	v_add_f32_e32 v176, v176, v185
	s_waitcnt lgkmcnt(3)
	v_mfma_f32_32x32x16_bf16 v[18:33], v[106:109], v[82:85], v[18:33]
	v_add_f32_e32 v176, v176, v186
	v_add_f32_e32 v176, v176, v187
	v_add_f32_e32 v176, v176, v194
	v_add_f32_e32 v176, v176, v195
	s_waitcnt lgkmcnt(2)
	v_mfma_f32_32x32x16_bf16 v[2:17], v[110:113], v[82:85], v[2:17]
	v_cvt_pk_bf16_f32 v86, v196, v197
	v_cvt_pk_bf16_f32 v87, v198, v199
	v_cvt_pk_bf16_f32 v88, v138, v139
	v_cvt_pk_bf16_f32 v89, v140, v141
	v_add_f32_e32 v176, v176, v134
	v_add_f32_e32 v176, v176, v135
	v_add_f32_e32 v176, v176, v136
	v_add_f32_e32 v176, v176, v137
	s_waitcnt lgkmcnt(1)
	v_mfma_f32_32x32x16_bf16 v[18:33], v[122:125], v[86:89], v[18:33]
	v_add_f32_e32 v176, v176, v196
	v_add_f32_e32 v176, v176, v197
	v_add_f32_e32 v176, v176, v198
	v_add_f32_e32 v176, v176, v199
	s_waitcnt lgkmcnt(0)
	v_mfma_f32_32x32x16_bf16 v[2:17], v[126:129], v[86:89], v[2:17]
	v_add_f32_e32 v176, v176, v138
	v_add_f32_e32 v176, v176, v139
	v_add_f32_e32 v176, v176, v140
	v_add_f32_e32 v176, v176, v141
	s_setprio 0
	ds_read_b128 v[106:109], v165 offset:27680
	ds_read_b128 v[122:125], v165 offset:32288
	s_cmp_lg_u32 s25, 4
	s_cselect_b32 s25, s28, 0
	s_waitcnt lgkmcnt(2)
	v_mfma_f32_32x32x16_bf16 v[138:153], v[240:243], v[158:161], v[34:49]
	v_exp_f32_e32 v126, v66
	v_exp_f32_e32 v127, v67
	v_exp_f32_e32 v128, v68
	v_exp_f32_e32 v129, v69
	v_exp_f32_e32 v130, v70
	v_exp_f32_e32 v131, v71
	v_exp_f32_e32 v132, v72
	v_exp_f32_e32 v133, v73
	s_waitcnt lgkmcnt(1)
	v_mfma_f32_32x32x16_bf16 v[82:97], v[244:247], v[158:161], v[34:49]
	v_exp_f32_e32 v134, v74
	v_exp_f32_e32 v135, v75
	v_exp_f32_e32 v136, v76
	v_exp_f32_e32 v137, v77
	v_exp_f32_e32 v177, v78
	v_exp_f32_e32 v178, v79
	v_exp_f32_e32 v179, v80
	v_exp_f32_e32 v185, v81
	v_mfma_f32_32x32x16_bf16 v[138:153], v[106:109], v[154:157], v[138:153]
	v_exp_f32_e32 v80, v50
	v_exp_f32_e32 v81, v51
	v_exp_f32_e32 v186, v52
	v_exp_f32_e32 v187, v53
	v_exp_f32_e32 v194, v54
	v_exp_f32_e32 v195, v55
	v_exp_f32_e32 v196, v56
	v_exp_f32_e32 v197, v57
	s_waitcnt lgkmcnt(0)
	v_mfma_f32_32x32x16_bf16 v[82:97], v[122:125], v[154:157], v[82:97]
	v_exp_f32_e32 v198, v58
	v_exp_f32_e32 v199, v59
	v_exp_f32_e32 v200, v60
	v_exp_f32_e32 v201, v61
	v_exp_f32_e32 v122, v62
	v_exp_f32_e32 v123, v63
	v_exp_f32_e32 v124, v64
	v_exp_f32_e32 v125, v65
	s_cmp_gt_i32 s25, 2
	s_cselect_b32 s26, -3, 2
	s_add_i32 s26, s26, s25
	s_mulk_i32 s26, 0x2400
	v_add_u32_e32 v50, s26, v182
	s_add_i32 s26, s25, 1
	s_cmp_lg_u32 s25, 4
	s_cselect_b32 s25, s26, 0
	s_add_i32 s26, s23, -1
	s_min_u32 s26, s26, s13
	s_lshl_b32 s92, s26, 13
	s_waitcnt vmcnt(3)
	ds_write_b128 v182, v[118:121] offset:9216
	s_waitcnt vmcnt(2)
	ds_write_b128 v50, v[114:117] offset:36864
	s_add_u32 vcc_lo, s100, s92
	s_addc_u32 vcc_hi, s101, 0
	global_load_dwordx4 v[56:59], v248, vcc
	s_lshl_b32 s92, s27, 7
	s_add_u32 vcc_lo, s98, s92
	s_addc_u32 vcc_hi, s99, 0
	global_load_dwordx4 v[52:55], v249, vcc
	s_nop 0
	s_mul_i32 s27, s25, 0x2400
	s_add_i32 s28, s27, 0xffffdc00
	s_cmp_lg_u32 s25, 0
	s_cselect_b32 s28, s28, 0x9000
	v_add_u32_e32 v50, s28, v163
	ds_read_b128 v[60:63], v50 offset:36864
	ds_read_b128 v[64:67], v50 offset:36896
	ds_read_b128 v[68:71], v50 offset:41472
	ds_read_b128 v[72:75], v50 offset:41504
	ds_read_b128 v[76:79], v50 offset:36928
	ds_read_b128 v[106:109], v50 offset:36960
	ds_read_b128 v[110:113], v50 offset:41536
	ds_read_b128 v[114:117], v50 offset:41568
	s_setprio 3
	v_cvt_pk_bf16_f32 v118, v126, v127
	v_cvt_pk_bf16_f32 v119, v128, v129
	v_cvt_pk_bf16_f32 v120, v130, v131
	v_cvt_pk_bf16_f32 v121, v132, v133
	s_waitcnt lgkmcnt(7)
	s_nop 0
	v_mfma_f32_32x32x16_bf16 v[18:33], v[60:63], v[118:121], v[18:33]
	v_add_f32_e32 v50, v126, v127
	v_add_f32_e32 v50, v50, v128
	v_add_f32_e32 v50, v50, v129
	s_waitcnt lgkmcnt(5)
	v_mfma_f32_32x32x16_bf16 v[2:17], v[68:71], v[118:121], v[2:17]
	v_cvt_pk_bf16_f32 v60, v134, v135
	v_cvt_pk_bf16_f32 v61, v136, v137
	v_cvt_pk_bf16_f32 v62, v177, v178
	v_cvt_pk_bf16_f32 v63, v179, v185
	v_add_f32_e32 v50, v50, v130
	v_add_f32_e32 v50, v50, v131
	v_add_f32_e32 v50, v50, v132
	v_add_f32_e32 v50, v50, v133
	s_nop 0
	v_mfma_f32_32x32x16_bf16 v[18:33], v[64:67], v[60:63], v[18:33]
	v_add_f32_e32 v50, v50, v134
	v_add_f32_e32 v50, v50, v135
	v_add_f32_e32 v50, v50, v136
	v_add_f32_e32 v50, v50, v137
	s_waitcnt lgkmcnt(4)
	v_mfma_f32_32x32x16_bf16 v[2:17], v[72:75], v[60:63], v[2:17]
	v_cvt_pk_bf16_f32 v64, v80, v81
	v_cvt_pk_bf16_f32 v65, v186, v187
	v_cvt_pk_bf16_f32 v66, v194, v195
	v_cvt_pk_bf16_f32 v67, v196, v197
	v_add_f32_e32 v50, v50, v177
	v_add_f32_e32 v50, v50, v178
	v_add_f32_e32 v50, v50, v179
	v_add_f32_e32 v50, v50, v185
	s_waitcnt lgkmcnt(3)
	v_mfma_f32_32x32x16_bf16 v[18:33], v[76:79], v[64:67], v[18:33]
	v_add_f32_e32 v50, v50, v80
	v_add_f32_e32 v50, v50, v81
	v_add_f32_e32 v50, v50, v186
	v_add_f32_e32 v50, v50, v187
	s_waitcnt lgkmcnt(1)
	v_mfma_f32_32x32x16_bf16 v[2:17], v[110:113], v[64:67], v[2:17]
	v_cvt_pk_bf16_f32 v60, v198, v199
	v_cvt_pk_bf16_f32 v61, v200, v201
	v_cvt_pk_bf16_f32 v62, v122, v123
	v_cvt_pk_bf16_f32 v63, v124, v125
	v_add_f32_e32 v50, v50, v194
	v_add_f32_e32 v50, v50, v195
	v_add_f32_e32 v50, v50, v196
	v_add_f32_e32 v50, v50, v197
	s_nop 0
	v_mfma_f32_32x32x16_bf16 v[18:33], v[106:109], v[60:63], v[18:33]
	v_add_f32_e32 v50, v50, v198
	v_add_f32_e32 v50, v50, v199
	v_add_f32_e32 v50, v50, v200
	v_add_f32_e32 v50, v50, v201
	s_waitcnt lgkmcnt(0)
	v_mfma_f32_32x32x16_bf16 v[2:17], v[114:117], v[60:63], v[2:17]
	v_add_f32_e32 v50, v50, v122
	v_add_f32_e32 v50, v50, v123
	v_add_f32_e32 v50, v50, v124
	v_add_f32_e32 v50, v50, v125
	s_setprio 2
	s_waitcnt lgkmcnt(0)
	s_barrier
	ds_read_b128 v[240:243], v165
	ds_read_b128 v[244:247], v165 offset:4608
	ds_read_b128 v[68:71], v165 offset:32
	ds_read_b128 v[72:75], v165 offset:4640
	v_add_f32_e32 v1, v1, v176
	v_exp_f32_e32 v176, v138
	v_exp_f32_e32 v177, v139
	v_exp_f32_e32 v178, v140
	v_exp_f32_e32 v179, v141
	v_exp_f32_e32 v185, v142
	v_exp_f32_e32 v186, v143
	v_exp_f32_e32 v187, v144
	v_exp_f32_e32 v194, v145
	s_waitcnt lgkmcnt(2)
	v_mfma_f32_32x32x16_bf16 v[122:137], v[240:243], v[158:161], v[34:49]
	v_mfma_f32_32x32x16_bf16 v[106:121], v[244:247], v[158:161], v[34:49]
	v_exp_f32_e32 v195, v146
	v_exp_f32_e32 v196, v147
	v_exp_f32_e32 v197, v148
	v_exp_f32_e32 v198, v149
	v_exp_f32_e32 v146, v150
	v_exp_f32_e32 v147, v151
	v_exp_f32_e32 v148, v152
	v_exp_f32_e32 v149, v153
	s_waitcnt lgkmcnt(1)
	v_mfma_f32_32x32x16_bf16 v[122:137], v[68:71], v[154:157], v[122:137]
	v_exp_f32_e32 v150, v82
	v_exp_f32_e32 v151, v83
	v_exp_f32_e32 v152, v84
	v_exp_f32_e32 v153, v85
	v_exp_f32_e32 v199, v86
	v_exp_f32_e32 v200, v87
	v_exp_f32_e32 v201, v88
	v_exp_f32_e32 v202, v89
	s_waitcnt lgkmcnt(0)
	v_mfma_f32_32x32x16_bf16 v[106:121], v[72:75], v[154:157], v[106:121]
	v_exp_f32_e32 v203, v90
	v_exp_f32_e32 v204, v91
	v_exp_f32_e32 v205, v92
	v_exp_f32_e32 v206, v93
	v_exp_f32_e32 v207, v94
	v_exp_f32_e32 v208, v95
	v_exp_f32_e32 v209, v96
	v_exp_f32_e32 v210, v97
	v_add_u32_e32 v88, s27, v163
	ds_read_b128 v[240:243], v165 offset:9216
	ds_read_b128 v[244:247], v165 offset:13824
	ds_read_b128 v[60:63], v88 offset:41472
	ds_read_b128 v[64:67], v88 offset:36864
	ds_read_b128 v[68:71], v88 offset:36896
	ds_read_b128 v[72:75], v88 offset:41504
	ds_read_b128 v[76:79], v88 offset:36928
	ds_read_b128 v[80:83], v88 offset:41536
	ds_read_b128 v[84:87], v88 offset:36960
	ds_read_b128 v[88:91], v88 offset:41568
	s_cmp_gt_i32 s25, 2
	s_cselect_b32 s28, -3, 2
	s_add_i32 s28, s28, s25
	s_mulk_i32 s28, 0x2400
	s_min_u32 s27, s23, s13
	v_add_u32_e32 v51, s28, v182
	s_lshl_b32 s92, s27, 13
	s_waitcnt vmcnt(3)
	ds_write_b128 v182, v[98:101] offset:18432
	s_waitcnt vmcnt(2)
	ds_write_b128 v51, v[102:105] offset:36864
	v_add_f32_e32 v1, v1, v50
	s_add_u32 vcc_lo, s100, s92
	s_addc_u32 vcc_hi, s101, 0
	global_load_dwordx4 v[138:141], v248, vcc
	s_lshl_b32 s92, s26, 7
	s_add_u32 vcc_lo, s98, s92
	s_addc_u32 vcc_hi, s99, 0
	global_load_dwordx4 v[142:145], v249, vcc
	s_setprio 1
	v_mov_b32_e32 v51, v122
	v_cvt_pk_bf16_f32 v92, v176, v177
	v_cvt_pk_bf16_f32 v93, v178, v179
	v_cvt_pk_bf16_f32 v94, v185, v186
	v_cvt_pk_bf16_f32 v95, v187, v194
	s_waitcnt lgkmcnt(8)
	s_nop 0
	v_mfma_f32_32x32x16_bf16 v[18:33], v[64:67], v[92:95], v[18:33]
	v_max3_f32 v51, v51, v123, v124
	v_max3_f32 v51, v51, v125, v126
	v_add_f32_e32 v50, v176, v177
	v_add_f32_e32 v50, v50, v178
	v_add_f32_e32 v50, v50, v179
	s_nop 0
	v_mfma_f32_32x32x16_bf16 v[2:17], v[60:63], v[92:95], v[2:17]
	v_cvt_pk_bf16_f32 v64, v195, v196
	v_cvt_pk_bf16_f32 v65, v197, v198
	v_cvt_pk_bf16_f32 v66, v146, v147
	v_cvt_pk_bf16_f32 v67, v148, v149
	v_max3_f32 v51, v51, v127, v128
	v_max3_f32 v51, v51, v129, v130
	v_add_f32_e32 v50, v50, v185
	v_add_f32_e32 v50, v50, v186
	v_add_f32_e32 v50, v50, v187
	v_add_f32_e32 v50, v50, v194
	s_waitcnt lgkmcnt(7)
	v_mfma_f32_32x32x16_bf16 v[18:33], v[68:71], v[64:67], v[18:33]
	v_max3_f32 v51, v51, v131, v132
	v_max3_f32 v51, v51, v133, v134
	v_add_f32_e32 v50, v50, v195
	v_add_f32_e32 v50, v50, v196
	v_add_f32_e32 v50, v50, v197
	v_add_f32_e32 v50, v50, v198
	s_waitcnt lgkmcnt(6)
	v_mfma_f32_32x32x16_bf16 v[2:17], v[72:75], v[64:67], v[2:17]
	v_cvt_pk_bf16_f32 v60, v150, v151
	v_cvt_pk_bf16_f32 v61, v152, v153
	v_cvt_pk_bf16_f32 v62, v199, v200
	v_cvt_pk_bf16_f32 v63, v201, v202
	v_max3_f32 v51, v51, v135, v136
	v_max3_f32 v51, v51, v137, v106
	v_add_f32_e32 v50, v50, v146
	v_add_f32_e32 v50, v50, v147
	v_add_f32_e32 v50, v50, v148
	v_add_f32_e32 v50, v50, v149
	s_waitcnt lgkmcnt(5)
	v_mfma_f32_32x32x16_bf16 v[18:33], v[76:79], v[60:63], v[18:33]
	v_max3_f32 v51, v51, v107, v108
	v_max3_f32 v51, v51, v109, v110
	v_add_f32_e32 v50, v50, v150
	v_add_f32_e32 v50, v50, v151
	v_add_f32_e32 v50, v50, v152
	v_add_f32_e32 v50, v50, v153
	s_waitcnt lgkmcnt(4)
	v_mfma_f32_32x32x16_bf16 v[2:17], v[80:83], v[60:63], v[2:17]
	v_cvt_pk_bf16_f32 v64, v203, v204
	v_cvt_pk_bf16_f32 v65, v205, v206
	v_cvt_pk_bf16_f32 v66, v207, v208
	v_cvt_pk_bf16_f32 v67, v209, v210
	v_max3_f32 v51, v51, v111, v112
	v_max3_f32 v51, v51, v113, v114
	v_add_f32_e32 v50, v50, v199
	v_add_f32_e32 v50, v50, v200
	v_add_f32_e32 v50, v50, v201
	v_add_f32_e32 v50, v50, v202
	s_waitcnt lgkmcnt(3)
	v_mfma_f32_32x32x16_bf16 v[18:33], v[84:87], v[64:67], v[18:33]
	v_max3_f32 v51, v51, v115, v116
	v_max3_f32 v51, v51, v117, v118
	v_add_f32_e32 v50, v50, v203
	v_add_f32_e32 v50, v50, v204
	v_add_f32_e32 v50, v50, v205
	v_add_f32_e32 v50, v50, v206
	s_waitcnt lgkmcnt(2)
	v_mfma_f32_32x32x16_bf16 v[2:17], v[88:91], v[64:67], v[2:17]
	v_max3_f32 v51, v51, v119, v120
	v_max3_f32 v51, v51, v121, v121
	v_add_f32_e32 v50, v50, v207
	v_add_f32_e32 v50, v50, v208
	v_add_f32_e32 v50, v50, v209
	v_add_f32_e32 v50, v50, v210
	s_setprio 0
	ds_read_b128 v[146:149], v165 offset:9248
	ds_read_b128 v[60:63], v165 offset:13856
	v_add_f32_e32 v50, v1, v50
	v_mov_b32_e32 v1, v51
	s_nop 1
	v_permlane32_swap_b32_e32 v51, v1
	v_max_f32_e32 v1, v1, v1
	v_max_f32_e32 v51, v51, v51
	v_max_f32_e32 v1, v51, v1
	v_cmp_lt_f32_e32 vcc, s52, v1
	s_cbranch_vccz .LBB0_643
	v_max_f32_e32 v1, v1, v1
	v_max_f32_e32 v68, 0, v1
	v_add_f32_e32 v183, v183, v68
	v_xor_b32_e32 v34, 0x80000000, v183
	v_pk_add_f32 v[122:123], v[122:123], v[68:69] op_sel_hi:[1,0] neg_lo:[0,1] neg_hi:[0,1]
	v_pk_add_f32 v[106:107], v[106:107], v[68:69] op_sel_hi:[1,0] neg_lo:[0,1] neg_hi:[0,1]
	v_pk_add_f32 v[124:125], v[124:125], v[68:69] op_sel_hi:[1,0] neg_lo:[0,1] neg_hi:[0,1]
	v_pk_add_f32 v[108:109], v[108:109], v[68:69] op_sel_hi:[1,0] neg_lo:[0,1] neg_hi:[0,1]
	v_pk_add_f32 v[126:127], v[126:127], v[68:69] op_sel_hi:[1,0] neg_lo:[0,1] neg_hi:[0,1]
	v_pk_add_f32 v[110:111], v[110:111], v[68:69] op_sel_hi:[1,0] neg_lo:[0,1] neg_hi:[0,1]
	v_pk_add_f32 v[128:129], v[128:129], v[68:69] op_sel_hi:[1,0] neg_lo:[0,1] neg_hi:[0,1]
	v_pk_add_f32 v[112:113], v[112:113], v[68:69] op_sel_hi:[1,0] neg_lo:[0,1] neg_hi:[0,1]
	v_pk_add_f32 v[130:131], v[130:131], v[68:69] op_sel_hi:[1,0] neg_lo:[0,1] neg_hi:[0,1]
	v_pk_add_f32 v[114:115], v[114:115], v[68:69] op_sel_hi:[1,0] neg_lo:[0,1] neg_hi:[0,1]
	v_pk_add_f32 v[132:133], v[132:133], v[68:69] op_sel_hi:[1,0] neg_lo:[0,1] neg_hi:[0,1]
	v_pk_add_f32 v[116:117], v[116:117], v[68:69] op_sel_hi:[1,0] neg_lo:[0,1] neg_hi:[0,1]
	v_pk_add_f32 v[134:135], v[134:135], v[68:69] op_sel_hi:[1,0] neg_lo:[0,1] neg_hi:[0,1]
	v_pk_add_f32 v[118:119], v[118:119], v[68:69] op_sel_hi:[1,0] neg_lo:[0,1] neg_hi:[0,1]
	v_pk_add_f32 v[136:137], v[136:137], v[68:69] op_sel_hi:[1,0] neg_lo:[0,1] neg_hi:[0,1]
	v_pk_add_f32 v[120:121], v[120:121], v[68:69] op_sel_hi:[1,0] neg_lo:[0,1] neg_hi:[0,1]
	v_exp_f32_e64 v68, -v68
	v_mov_b32_e32 v35, v34
	v_mov_b32_e32 v36, v34
	v_mov_b32_e32 v37, v34
	v_mov_b32_e32 v38, v34
	v_mov_b32_e32 v39, v34
	v_mov_b32_e32 v40, v34
	v_mov_b32_e32 v41, v34
	v_mov_b32_e32 v42, v34
	v_mov_b32_e32 v43, v34
	v_mov_b32_e32 v44, v34
	v_mov_b32_e32 v45, v34
	v_mov_b32_e32 v46, v34
	v_mov_b32_e32 v47, v34
	v_mov_b32_e32 v48, v34
	v_mov_b32_e32 v49, v34
	s_nop 11
	v_pk_mul_f32 v[32:33], v[32:33], v[68:69] op_sel_hi:[1,0]
	v_pk_mul_f32 v[30:31], v[30:31], v[68:69] op_sel_hi:[1,0]
	v_pk_mul_f32 v[28:29], v[28:29], v[68:69] op_sel_hi:[1,0]
	v_pk_mul_f32 v[26:27], v[26:27], v[68:69] op_sel_hi:[1,0]
	v_pk_mul_f32 v[24:25], v[24:25], v[68:69] op_sel_hi:[1,0]
	v_pk_mul_f32 v[22:23], v[22:23], v[68:69] op_sel_hi:[1,0]
	v_pk_mul_f32 v[20:21], v[20:21], v[68:69] op_sel_hi:[1,0]
	v_pk_mul_f32 v[18:19], v[18:19], v[68:69] op_sel_hi:[1,0]
	v_pk_mul_f32 v[16:17], v[16:17], v[68:69] op_sel_hi:[1,0]
	v_pk_mul_f32 v[14:15], v[14:15], v[68:69] op_sel_hi:[1,0]
	v_pk_mul_f32 v[12:13], v[12:13], v[68:69] op_sel_hi:[1,0]
	v_pk_mul_f32 v[10:11], v[10:11], v[68:69] op_sel_hi:[1,0]
	v_pk_mul_f32 v[8:9], v[8:9], v[68:69] op_sel_hi:[1,0]
	v_pk_mul_f32 v[6:7], v[6:7], v[68:69] op_sel_hi:[1,0]
	v_pk_mul_f32 v[4:5], v[4:5], v[68:69] op_sel_hi:[1,0]
	v_pk_mul_f32 v[2:3], v[2:3], v[68:69] op_sel_hi:[1,0]
	v_mul_f32_e32 v50, v50, v68

.LBB0_661:
	s_add_i32 s26, s13, -7
	s_lshl_b32 s92, s26, 13
	s_add_u32 vcc_lo, s100, s92
	s_addc_u32 vcc_hi, s101, 0
	global_load_dwordx4 v[2:5], v248, vcc
	s_add_i32 s26, s13, -8
	s_lshl_b32 s92, s26, 7
	s_add_u32 vcc_lo, s98, s92
	s_addc_u32 vcc_hi, s99, 0
	global_load_dwordx4 v[6:9], v249, vcc
	s_mul_i32 s28, s27, 0x2400
	s_add_i32 s26, s13, -7
	s_add_i32 s29, s28, 0xffffdc00
	s_cmp_lg_u32 s27, 0
	s_cselect_b32 s29, s29, 0x9000
	v_add_u32_e32 v1, s29, v195
	ds_read_b128 v[10:13], v1 offset:36864
	ds_read_b128 v[66:69], v1 offset:36896
	ds_read_b128 v[70:73], v1 offset:41472
	ds_read_b128 v[74:77], v1 offset:41504
	ds_read_b128 v[128:131], v1 offset:36928
	ds_read_b128 v[132:135], v1 offset:36960
	ds_read_b128 v[148:151], v1 offset:41536
	ds_read_b128 v[160:163], v1 offset:41568
	s_setprio 3
	v_cvt_pk_bf16_f32 v210, v116, v117
	v_cvt_pk_bf16_f32 v211, v118, v119
	v_cvt_pk_bf16_f32 v212, v112, v113
	v_cvt_pk_bf16_f32 v213, v114, v115
	s_waitcnt lgkmcnt(7)
	s_nop 0
	v_mfma_f32_32x32x16_bf16 v[16:31], v[10:13], v[210:213], v[16:31]
	v_add_f32_e32 v1, v116, v117
	v_add_f32_e32 v1, v1, v118
	v_add_f32_e32 v1, v1, v119
	s_waitcnt lgkmcnt(5)
	v_mfma_f32_32x32x16_bf16 v[32:47], v[70:73], v[210:213], v[32:47]
	v_cvt_pk_bf16_f32 v10, v187, v186
	v_cvt_pk_bf16_f32 v11, v185, v184
	v_cvt_pk_bf16_f32 v12, v147, v146
	v_cvt_pk_bf16_f32 v13, v145, v144
	v_add_f32_e32 v1, v1, v112
	v_add_f32_e32 v1, v1, v113
	v_add_f32_e32 v1, v1, v114
	v_add_f32_e32 v1, v1, v115
	s_nop 0
	v_mfma_f32_32x32x16_bf16 v[16:31], v[66:69], v[10:13], v[16:31]
	v_add_f32_e32 v1, v1, v187
	v_add_f32_e32 v1, v1, v186
	v_add_f32_e32 v1, v1, v185
	v_add_f32_e32 v1, v1, v184
	s_waitcnt lgkmcnt(4)
	v_mfma_f32_32x32x16_bf16 v[32:47], v[74:77], v[10:13], v[32:47]
	v_cvt_pk_bf16_f32 v66, v143, v142
	v_cvt_pk_bf16_f32 v67, v141, v140
	v_cvt_pk_bf16_f32 v68, v139, v138
	v_cvt_pk_bf16_f32 v69, v137, v136
	v_add_f32_e32 v1, v1, v147
	v_add_f32_e32 v1, v1, v146
	v_add_f32_e32 v1, v1, v145
	v_add_f32_e32 v1, v1, v144
	s_waitcnt lgkmcnt(3)
	v_mfma_f32_32x32x16_bf16 v[16:31], v[128:131], v[66:69], v[16:31]
	v_add_f32_e32 v1, v1, v143
	v_add_f32_e32 v1, v1, v142
	v_add_f32_e32 v1, v1, v141
	v_add_f32_e32 v1, v1, v140
	s_waitcnt lgkmcnt(1)
	v_mfma_f32_32x32x16_bf16 v[32:47], v[148:151], v[66:69], v[32:47]
	v_cvt_pk_bf16_f32 v10, v123, v122
	v_cvt_pk_bf16_f32 v11, v121, v120
	v_cvt_pk_bf16_f32 v12, v127, v126
	v_cvt_pk_bf16_f32 v13, v125, v124
	v_add_f32_e32 v1, v1, v139
	v_add_f32_e32 v1, v1, v138
	v_add_f32_e32 v1, v1, v137
	v_add_f32_e32 v1, v1, v136
	s_nop 0
	v_mfma_f32_32x32x16_bf16 v[16:31], v[132:135], v[10:13], v[16:31]
	v_add_f32_e32 v1, v1, v123
	v_add_f32_e32 v1, v1, v122
	v_add_f32_e32 v1, v1, v121
	v_add_f32_e32 v1, v1, v120
	s_waitcnt lgkmcnt(0)
	v_mfma_f32_32x32x16_bf16 v[32:47], v[160:163], v[10:13], v[32:47]
	v_add_f32_e32 v1, v1, v127
	v_add_f32_e32 v1, v1, v126
	v_add_f32_e32 v1, v1, v125
	v_add_f32_e32 v1, v1, v124
	s_setprio 2
	s_waitcnt lgkmcnt(0)
	s_barrier
	ds_read_b128 v[240:243], v195 offset:18432
	ds_read_b128 v[244:247], v195 offset:23040
	ds_read_b128 v[66:69], v195 offset:18464
	ds_read_b128 v[74:77], v195 offset:23072
	ds_read_b128 v[144:147], v195 offset:18496
	ds_read_b128 v[148:151], v195 offset:18528
	ds_read_b128 v[160:163], v195 offset:23104
	ds_read_b128 v[184:187], v195 offset:23136
	v_exp_f32_e32 v166, v96
	v_exp_f32_e32 v167, v97
	v_exp_f32_e32 v210, v98
	v_exp_f32_e32 v211, v99
	s_waitcnt lgkmcnt(6)
	v_mfma_f32_32x32x16_bf16 v[128:143], v[240:243], v[180:183], v[48:63]
	s_waitcnt lgkmcnt(5)
	v_mfma_f32_32x32x16_bf16 v[112:127], v[244:247], v[180:183], v[48:63]
	v_exp_f32_e32 v212, v100
	v_exp_f32_e32 v213, v101
	v_exp_f32_e32 v214, v102
	v_exp_f32_e32 v215, v103
	v_mfma_f32_32x32x16_bf16 v[128:143], v[66:69], v[176:179], v[128:143]
	v_exp_f32_e32 v100, v104
	v_exp_f32_e32 v101, v105
	v_exp_f32_e32 v102, v106
	v_exp_f32_e32 v103, v107
	s_waitcnt lgkmcnt(4)
	v_mfma_f32_32x32x16_bf16 v[112:127], v[74:77], v[176:179], v[112:127]
	v_exp_f32_e32 v104, v108
	v_exp_f32_e32 v105, v109
	v_exp_f32_e32 v106, v110
	v_exp_f32_e32 v107, v111
	s_waitcnt lgkmcnt(3)
	v_mfma_f32_32x32x16_bf16 v[128:143], v[144:147], v[172:175], v[128:143]
	v_exp_f32_e32 v108, v80
	v_exp_f32_e32 v109, v81
	v_exp_f32_e32 v110, v82
	v_exp_f32_e32 v111, v83
	s_waitcnt lgkmcnt(1)
	v_mfma_f32_32x32x16_bf16 v[112:127], v[160:163], v[172:175], v[112:127]
	v_exp_f32_e32 v144, v84
	v_exp_f32_e32 v145, v85
	v_exp_f32_e32 v146, v86
	v_exp_f32_e32 v147, v87
	v_mfma_f32_32x32x16_bf16 v[128:143], v[148:151], v[168:171], v[128:143]
	v_exp_f32_e32 v216, v88
	v_exp_f32_e32 v217, v89
	v_exp_f32_e32 v218, v90
	v_exp_f32_e32 v219, v91
	s_waitcnt lgkmcnt(0)
	v_mfma_f32_32x32x16_bf16 v[112:127], v[184:187], v[168:171], v[112:127]
	v_exp_f32_e32 v148, v92
	v_exp_f32_e32 v149, v93
	v_exp_f32_e32 v150, v94
	v_exp_f32_e32 v151, v95
	v_add_f32_e32 v1, v64, v1
	v_add_u32_e32 v92, s28, v195
	ds_read_b128 v[240:243], v195 offset:27648
	ds_read_b128 v[244:247], v195 offset:32256
	ds_read_b128 v[64:67], v92 offset:41472
	ds_read_b128 v[68:71], v92 offset:36864
	ds_read_b128 v[72:75], v92 offset:36896
	ds_read_b128 v[76:79], v92 offset:41504
	ds_read_b128 v[80:83], v92 offset:36928
	ds_read_b128 v[84:87], v92 offset:41536
	ds_read_b128 v[88:91], v92 offset:36960
	ds_read_b128 v[92:95], v92 offset:41568
	s_cmp_gt_i32 s27, 2
	s_cselect_b32 s29, -3, 2
	s_add_i32 s29, s29, s27
	s_add_i32 s28, s13, -6
	s_mulk_i32 s29, 0x2400
	s_min_u32 s28, s28, s12
	v_add_u32_e32 v10, s29, v208
	s_min_u32 s26, s26, s12
	s_lshl_b32 s92, s28, 13
	s_waitcnt vmcnt(3)
	ds_write_b128 v208, v[152:155]
	s_waitcnt vmcnt(2)
	ds_write_b128 v10, v[156:159] offset:36864
	s_add_u32 vcc_lo, s100, s92
	s_addc_u32 vcc_hi, s101, 0
	global_load_dwordx4 v[10:13], v248, vcc
	s_lshl_b32 s92, s26, 7
	s_add_u32 vcc_lo, s98, s92
	s_addc_u32 vcc_hi, s99, 0
	global_load_dwordx4 v[160:163], v249, vcc
	s_add_i32 s29, s27, 1
	s_setprio 1
	v_cvt_pk_bf16_f32 v96, v166, v167
	v_cvt_pk_bf16_f32 v97, v210, v211
	v_cvt_pk_bf16_f32 v98, v212, v213
	v_cvt_pk_bf16_f32 v99, v214, v215
	s_waitcnt lgkmcnt(8)
	s_nop 0
	v_mfma_f32_32x32x16_bf16 v[16:31], v[68:71], v[96:99], v[16:31]
	v_add_f32_e32 v184, v166, v167
	v_add_f32_e32 v184, v184, v210
	v_add_f32_e32 v184, v184, v211
	s_nop 0
	v_mfma_f32_32x32x16_bf16 v[32:47], v[64:67], v[96:99], v[32:47]
	v_cvt_pk_bf16_f32 v68, v100, v101
	v_cvt_pk_bf16_f32 v69, v102, v103
	v_cvt_pk_bf16_f32 v70, v104, v105
	v_cvt_pk_bf16_f32 v71, v106, v107
	v_add_f32_e32 v184, v184, v212
	v_add_f32_e32 v184, v184, v213
	v_add_f32_e32 v184, v184, v214
	v_add_f32_e32 v184, v184, v215
	s_waitcnt lgkmcnt(7)
	v_mfma_f32_32x32x16_bf16 v[16:31], v[72:75], v[68:71], v[16:31]
	v_add_f32_e32 v184, v184, v100
	v_add_f32_e32 v184, v184, v101
	v_add_f32_e32 v184, v184, v102
	v_add_f32_e32 v184, v184, v103
	s_waitcnt lgkmcnt(6)
	v_mfma_f32_32x32x16_bf16 v[32:47], v[76:79], v[68:71], v[32:47]
	v_cvt_pk_bf16_f32 v64, v108, v109
	v_cvt_pk_bf16_f32 v65, v110, v111
	v_cvt_pk_bf16_f32 v66, v144, v145
	v_cvt_pk_bf16_f32 v67, v146, v147
	v_add_f32_e32 v184, v184, v104
	v_add_f32_e32 v184, v184, v105
	v_add_f32_e32 v184, v184, v106
	v_add_f32_e32 v184, v184, v107
	s_waitcnt lgkmcnt(5)
	v_mfma_f32_32x32x16_bf16 v[16:31], v[80:83], v[64:67], v[16:31]
	v_add_f32_e32 v184, v184, v108
	v_add_f32_e32 v184, v184, v109
	v_add_f32_e32 v184, v184, v110
	v_add_f32_e32 v184, v184, v111
	s_waitcnt lgkmcnt(4)
	v_mfma_f32_32x32x16_bf16 v[32:47], v[84:87], v[64:67], v[32:47]
	v_cvt_pk_bf16_f32 v68, v216, v217
	v_cvt_pk_bf16_f32 v69, v218, v219
	v_cvt_pk_bf16_f32 v70, v148, v149
	v_cvt_pk_bf16_f32 v71, v150, v151
	v_add_f32_e32 v184, v184, v144
	v_add_f32_e32 v184, v184, v145
	v_add_f32_e32 v184, v184, v146
	v_add_f32_e32 v184, v184, v147
	s_waitcnt lgkmcnt(3)
	v_mfma_f32_32x32x16_bf16 v[16:31], v[88:91], v[68:71], v[16:31]
	v_add_f32_e32 v184, v184, v216
	v_add_f32_e32 v184, v184, v217
	v_add_f32_e32 v184, v184, v218
	v_add_f32_e32 v184, v184, v219
	s_waitcnt lgkmcnt(2)
	v_mfma_f32_32x32x16_bf16 v[32:47], v[92:95], v[68:71], v[32:47]
	v_add_f32_e32 v184, v184, v148
	v_add_f32_e32 v184, v184, v149
	v_add_f32_e32 v184, v184, v150
	v_add_f32_e32 v184, v184, v151
	s_setprio 0
	ds_read_b128 v[68:71], v195 offset:27680
	ds_read_b128 v[76:79], v195 offset:32288
	ds_read_b128 v[80:83], v195 offset:27712
	ds_read_b128 v[84:87], v195 offset:27744
	ds_read_b128 v[88:91], v195 offset:32320
	ds_read_b128 v[92:95], v195 offset:32352
	s_cmp_lg_u32 s27, 4
	s_cselect_b32 s26, s29, 0
	s_waitcnt lgkmcnt(6)
	v_mfma_f32_32x32x16_bf16 v[144:159], v[240:243], v[180:183], v[48:63]
	v_exp_f32_e32 v166, v128
	v_exp_f32_e32 v167, v129
	v_exp_f32_e32 v185, v130
	v_exp_f32_e32 v186, v131
	s_waitcnt lgkmcnt(5)
	v_mfma_f32_32x32x16_bf16 v[96:111], v[244:247], v[180:183], v[48:63]
	v_exp_f32_e32 v128, v132
	v_exp_f32_e32 v129, v133
	v_exp_f32_e32 v130, v134
	v_exp_f32_e32 v131, v135
	v_mfma_f32_32x32x16_bf16 v[144:159], v[68:71], v[176:179], v[144:159]
	v_exp_f32_e32 v132, v136
	v_exp_f32_e32 v133, v137
	v_exp_f32_e32 v134, v138
	v_exp_f32_e32 v135, v139
	s_waitcnt lgkmcnt(4)
	v_mfma_f32_32x32x16_bf16 v[96:111], v[76:79], v[176:179], v[96:111]
	v_exp_f32_e32 v136, v140
	v_exp_f32_e32 v137, v141
	v_exp_f32_e32 v138, v142
	v_exp_f32_e32 v139, v143
	s_waitcnt lgkmcnt(3)
	v_mfma_f32_32x32x16_bf16 v[144:159], v[80:83], v[172:175], v[144:159]
	v_exp_f32_e32 v140, v112
	v_exp_f32_e32 v141, v113
	v_exp_f32_e32 v142, v114
	v_exp_f32_e32 v143, v115
	s_waitcnt lgkmcnt(1)
	v_mfma_f32_32x32x16_bf16 v[96:111], v[88:91], v[172:175], v[96:111]
	v_exp_f32_e32 v187, v116
	v_exp_f32_e32 v210, v117
	v_exp_f32_e32 v211, v118
	v_exp_f32_e32 v212, v119
	v_mfma_f32_32x32x16_bf16 v[144:159], v[84:87], v[168:171], v[144:159]
	v_exp_f32_e32 v116, v120
	v_exp_f32_e32 v117, v121
	v_exp_f32_e32 v118, v122
	v_exp_f32_e32 v119, v123
	s_waitcnt lgkmcnt(0)
	v_mfma_f32_32x32x16_bf16 v[96:111], v[92:95], v[168:171], v[96:111]
	v_exp_f32_e32 v120, v124
	v_exp_f32_e32 v121, v125
	v_exp_f32_e32 v122, v126
	v_exp_f32_e32 v123, v127
	s_cmp_gt_i32 s26, 2
	s_cselect_b32 s27, -3, 2
	s_add_i32 s27, s27, s26
	s_mulk_i32 s27, 0x2400
	s_waitcnt vmcnt(3)
	ds_write_b128 v208, v[2:5] offset:9216
	v_add_u32_e32 v2, s27, v208
	s_add_i32 s27, s26, 1
	s_cmp_lg_u32 s26, 4
	s_cselect_b32 s26, s27, 0
	s_add_i32 s27, s13, -5
	s_min_u32 s27, s27, s12
	s_lshl_b32 s92, s27, 13
	s_waitcnt vmcnt(2)
	ds_write_b128 v2, v[6:9] offset:36864
	s_add_u32 vcc_lo, s100, s92
	s_addc_u32 vcc_hi, s101, 0
	global_load_dwordx4 v[6:9], v248, vcc
	s_lshl_b32 s92, s28, 7
	s_add_u32 vcc_lo, s98, s92
	s_addc_u32 vcc_hi, s99, 0
	global_load_dwordx4 v[2:5], v249, vcc
	s_nop 0
	s_mul_i32 s28, s26, 0x2400
	s_add_i32 s29, s28, 0xffffdc00
	s_cmp_lg_u32 s26, 0
	s_cselect_b32 s29, s29, 0x9000
	v_add_u32_e32 v92, s29, v195
	ds_read_b128 v[64:67], v92 offset:36864
	ds_read_b128 v[68:71], v92 offset:36896
	ds_read_b128 v[72:75], v92 offset:41472
	ds_read_b128 v[76:79], v92 offset:41504
	ds_read_b128 v[80:83], v92 offset:36928
	ds_read_b128 v[84:87], v92 offset:36960
	ds_read_b128 v[88:91], v92 offset:41536
	ds_read_b128 v[92:95], v92 offset:41568
	s_setprio 3
	v_cvt_pk_bf16_f32 v112, v166, v167
	v_cvt_pk_bf16_f32 v113, v185, v186
	v_cvt_pk_bf16_f32 v114, v128, v129
	v_cvt_pk_bf16_f32 v115, v130, v131
	v_add_f32_e32 v213, v166, v167
	v_add_f32_e32 v213, v213, v185
	v_add_f32_e32 v213, v213, v186
	v_add_f32_e32 v213, v213, v128
	v_add_f32_e32 v213, v213, v129
	v_add_f32_e32 v213, v213, v130
	v_add_f32_e32 v213, v213, v131
	s_waitcnt lgkmcnt(7)
	s_nop 0
	v_mfma_f32_32x32x16_bf16 v[16:31], v[64:67], v[112:115], v[16:31]
	s_waitcnt lgkmcnt(5)
	v_mfma_f32_32x32x16_bf16 v[32:47], v[72:75], v[112:115], v[32:47]
	v_cvt_pk_bf16_f32 v64, v132, v133
	v_cvt_pk_bf16_f32 v65, v134, v135
	v_cvt_pk_bf16_f32 v66, v136, v137
	v_cvt_pk_bf16_f32 v67, v138, v139
	s_nop 0
	v_mfma_f32_32x32x16_bf16 v[16:31], v[68:71], v[64:67], v[16:31]
	v_add_f32_e32 v213, v213, v132
	v_add_f32_e32 v213, v213, v133
	v_add_f32_e32 v213, v213, v134
	v_add_f32_e32 v213, v213, v135
	s_waitcnt lgkmcnt(4)
	v_mfma_f32_32x32x16_bf16 v[32:47], v[76:79], v[64:67], v[32:47]
	v_cvt_pk_bf16_f32 v68, v140, v141
	v_cvt_pk_bf16_f32 v69, v142, v143
	v_cvt_pk_bf16_f32 v70, v187, v210
	v_cvt_pk_bf16_f32 v71, v211, v212
	v_add_f32_e32 v213, v213, v136
	v_add_f32_e32 v213, v213, v137
	v_add_f32_e32 v213, v213, v138
	v_add_f32_e32 v213, v213, v139
	s_waitcnt lgkmcnt(3)
	v_mfma_f32_32x32x16_bf16 v[16:31], v[80:83], v[68:71], v[16:31]
	v_add_f32_e32 v213, v213, v140
	v_add_f32_e32 v213, v213, v141
	v_add_f32_e32 v213, v213, v142
	v_add_f32_e32 v213, v213, v143
	s_waitcnt lgkmcnt(1)
	v_mfma_f32_32x32x16_bf16 v[32:47], v[88:91], v[68:71], v[32:47]
	v_cvt_pk_bf16_f32 v64, v116, v117
	v_cvt_pk_bf16_f32 v65, v118, v119
	v_cvt_pk_bf16_f32 v66, v120, v121
	v_cvt_pk_bf16_f32 v67, v122, v123
	v_add_f32_e32 v213, v213, v187
	v_add_f32_e32 v213, v213, v210
	v_add_f32_e32 v213, v213, v211
	v_add_f32_e32 v213, v213, v212
	s_nop 0
	v_mfma_f32_32x32x16_bf16 v[16:31], v[84:87], v[64:67], v[16:31]
	v_add_f32_e32 v213, v213, v116
	v_add_f32_e32 v213, v213, v117
	v_add_f32_e32 v213, v213, v118
	v_add_f32_e32 v213, v213, v119
	s_waitcnt lgkmcnt(0)
	v_mfma_f32_32x32x16_bf16 v[32:47], v[92:95], v[64:67], v[32:47]
	v_add_f32_e32 v213, v213, v120
	v_add_f32_e32 v213, v213, v121
	v_add_f32_e32 v213, v213, v122
	v_add_f32_e32 v213, v213, v123
	s_setprio 2
	s_waitcnt lgkmcnt(0)
	s_barrier
	ds_read_b128 v[240:243], v195
	ds_read_b128 v[244:247], v195 offset:4608
	ds_read_b128 v[116:119], v195 offset:32
	ds_read_b128 v[120:123], v195 offset:4640
	ds_read_b128 v[124:127], v195 offset:64
	ds_read_b128 v[128:131], v195 offset:4672
	ds_read_b128 v[132:135], v195 offset:96
	ds_read_b128 v[136:139], v195 offset:4704
	v_add_f32_e32 v1, v1, v184
	v_exp_f32_e32 v140, v144
	v_exp_f32_e32 v141, v145
	v_exp_f32_e32 v142, v146
	v_exp_f32_e32 v143, v147
	s_waitcnt lgkmcnt(6)
	v_mfma_f32_32x32x16_bf16 v[80:95], v[240:243], v[180:183], v[48:63]
	v_mfma_f32_32x32x16_bf16 v[64:79], v[244:247], v[180:183], v[48:63]
	v_exp_f32_e32 v144, v148
	v_exp_f32_e32 v145, v149
	v_exp_f32_e32 v146, v150
	v_exp_f32_e32 v147, v151
	s_waitcnt lgkmcnt(5)
	v_mfma_f32_32x32x16_bf16 v[80:95], v[116:119], v[176:179], v[80:95]
	v_exp_f32_e32 v148, v152
	v_exp_f32_e32 v149, v153
	v_exp_f32_e32 v150, v154
	v_exp_f32_e32 v151, v155
	s_waitcnt lgkmcnt(4)
	v_mfma_f32_32x32x16_bf16 v[64:79], v[120:123], v[176:179], v[64:79]
	v_exp_f32_e32 v152, v156
	v_exp_f32_e32 v153, v157
	v_exp_f32_e32 v154, v158
	v_exp_f32_e32 v155, v159
	s_waitcnt lgkmcnt(3)
	v_mfma_f32_32x32x16_bf16 v[80:95], v[124:127], v[172:175], v[80:95]
	v_exp_f32_e32 v156, v96
	v_exp_f32_e32 v157, v97
	v_exp_f32_e32 v158, v98
	v_exp_f32_e32 v159, v99
	s_waitcnt lgkmcnt(2)
	v_mfma_f32_32x32x16_bf16 v[64:79], v[128:131], v[172:175], v[64:79]
	v_exp_f32_e32 v166, v100
	v_exp_f32_e32 v167, v101
	v_exp_f32_e32 v184, v102
	v_exp_f32_e32 v185, v103
	s_waitcnt lgkmcnt(1)
	v_mfma_f32_32x32x16_bf16 v[80:95], v[132:135], v[168:171], v[80:95]
	v_exp_f32_e32 v186, v104
	v_exp_f32_e32 v187, v105
	v_exp_f32_e32 v210, v106
	v_exp_f32_e32 v211, v107
	s_waitcnt lgkmcnt(0)
	v_mfma_f32_32x32x16_bf16 v[64:79], v[136:139], v[168:171], v[64:79]
	v_exp_f32_e32 v212, v108
	v_exp_f32_e32 v214, v109
	v_exp_f32_e32 v215, v110
	v_exp_f32_e32 v216, v111
	v_add_u32_e32 v124, s28, v195
	ds_read_b128 v[240:243], v195 offset:9216
	ds_read_b128 v[244:247], v195 offset:13824
	ds_read_b128 v[96:99], v124 offset:41472
	ds_read_b128 v[100:103], v124 offset:36864
	ds_read_b128 v[104:107], v124 offset:36896
	ds_read_b128 v[108:111], v124 offset:41504
	ds_read_b128 v[112:115], v124 offset:36928
	ds_read_b128 v[116:119], v124 offset:41536
	ds_read_b128 v[120:123], v124 offset:36960
	ds_read_b128 v[124:127], v124 offset:41568
	s_cmp_gt_i32 s26, 2
	s_cselect_b32 s29, -3, 2
	s_add_i32 s29, s29, s26
	s_mulk_i32 s29, 0x2400
	s_waitcnt vmcnt(3)
	ds_write_b128 v208, v[10:13] offset:18432
	v_add_u32_e32 v10, s29, v208
	s_mov_b32 s29, 0x1da90000
	s_waitcnt vmcnt(2)
	ds_write_b128 v10, v[160:163] offset:36864
	s_add_i32 s92, s13, -4
	s_lshl_b32 s92, s92, 13
	s_add_u32 vcc_lo, s100, s92
	s_addc_u32 vcc_hi, s101, 0
	global_load_dwordx4 v[128:131], v248, vcc
	s_lshl_b32 s92, s27, 7
	s_add_u32 vcc_lo, s98, s92
	s_addc_u32 vcc_hi, s99, 0
	global_load_dwordx4 v[10:13], v249, vcc
	v_add_f32_e32 v1, v1, v213
	s_add_i32 s28, s26, 1
	s_setprio 1
	v_cvt_pk_bf16_f32 v132, v140, v141
	v_cvt_pk_bf16_f32 v133, v142, v143
	v_cvt_pk_bf16_f32 v134, v144, v145
	v_cvt_pk_bf16_f32 v135, v146, v147
	s_waitcnt lgkmcnt(8)
	s_nop 0
	v_mfma_f32_32x32x16_bf16 v[16:31], v[100:103], v[132:135], v[16:31]
	v_add_f32_e32 v160, v140, v141
	v_add_f32_e32 v160, v160, v142
	v_add_f32_e32 v160, v160, v143
	s_nop 0
	v_mfma_f32_32x32x16_bf16 v[32:47], v[96:99], v[132:135], v[32:47]
	v_cvt_pk_bf16_f32 v100, v148, v149
	v_cvt_pk_bf16_f32 v101, v150, v151
	v_cvt_pk_bf16_f32 v102, v152, v153
	v_cvt_pk_bf16_f32 v103, v154, v155
	v_add_f32_e32 v160, v160, v144
	v_add_f32_e32 v160, v160, v145
	v_add_f32_e32 v160, v160, v146
	v_add_f32_e32 v160, v160, v147
	s_waitcnt lgkmcnt(7)
	v_mfma_f32_32x32x16_bf16 v[16:31], v[104:107], v[100:103], v[16:31]
	v_add_f32_e32 v160, v160, v148
	v_add_f32_e32 v160, v160, v149
	v_add_f32_e32 v160, v160, v150
	v_add_f32_e32 v160, v160, v151
	s_waitcnt lgkmcnt(6)
	v_mfma_f32_32x32x16_bf16 v[32:47], v[108:111], v[100:103], v[32:47]
	v_cvt_pk_bf16_f32 v96, v156, v157
	v_cvt_pk_bf16_f32 v97, v158, v159
	v_cvt_pk_bf16_f32 v98, v166, v167
	v_cvt_pk_bf16_f32 v99, v184, v185
	v_add_f32_e32 v160, v160, v152
	v_add_f32_e32 v160, v160, v153
	v_add_f32_e32 v160, v160, v154
	v_add_f32_e32 v160, v160, v155
	s_waitcnt lgkmcnt(5)
	v_mfma_f32_32x32x16_bf16 v[16:31], v[112:115], v[96:99], v[16:31]
	v_add_f32_e32 v160, v160, v156
	v_add_f32_e32 v160, v160, v157
	v_add_f32_e32 v160, v160, v158
	v_add_f32_e32 v160, v160, v159
	s_waitcnt lgkmcnt(4)
	v_mfma_f32_32x32x16_bf16 v[32:47], v[116:119], v[96:99], v[32:47]
	v_cvt_pk_bf16_f32 v100, v186, v187
	v_cvt_pk_bf16_f32 v101, v210, v211
	v_cvt_pk_bf16_f32 v102, v212, v214
	v_cvt_pk_bf16_f32 v103, v215, v216
	v_add_f32_e32 v160, v160, v166
	v_add_f32_e32 v160, v160, v167
	v_add_f32_e32 v160, v160, v184
	v_add_f32_e32 v160, v160, v185
	s_waitcnt lgkmcnt(3)
	v_mfma_f32_32x32x16_bf16 v[16:31], v[120:123], v[100:103], v[16:31]
	v_add_f32_e32 v160, v160, v186
	v_add_f32_e32 v160, v160, v187
	v_add_f32_e32 v160, v160, v210
	v_add_f32_e32 v160, v160, v211
	s_waitcnt lgkmcnt(2)
	v_mfma_f32_32x32x16_bf16 v[32:47], v[124:127], v[100:103], v[32:47]
	v_add_f32_e32 v160, v160, v212
	v_add_f32_e32 v160, v160, v214
	v_add_f32_e32 v160, v160, v215
	v_add_f32_e32 v160, v160, v216
	s_setprio 0
	ds_read_b128 v[132:135], v195 offset:9248
	ds_read_b128 v[140:143], v195 offset:13856
	ds_read_b128 v[144:147], v195 offset:9280
	ds_read_b128 v[148:151], v195 offset:9312
	ds_read_b128 v[152:155], v195 offset:13888
	ds_read_b128 v[156:159], v195 offset:13920
	s_cmp_lg_u32 s26, 4
	s_cselect_b32 s26, s28, 0
	s_waitcnt lgkmcnt(6)
	v_mfma_f32_32x32x16_bf16 v[112:127], v[240:243], v[180:183], v[48:63]
	v_exp_f32_e32 v161, v80
	v_exp_f32_e32 v162, v81
	v_exp_f32_e32 v163, v82
	v_exp_f32_e32 v164, v83
	s_waitcnt lgkmcnt(5)
	v_mfma_f32_32x32x16_bf16 v[96:111], v[244:247], v[180:183], v[48:63]
	v_exp_f32_e32 v165, v84
	v_exp_f32_e32 v166, v85
	v_exp_f32_e32 v167, v86
	v_exp_f32_e32 v184, v87
	v_mfma_f32_32x32x16_bf16 v[112:127], v[132:135], v[176:179], v[112:127]
	v_exp_f32_e32 v136, v88
	v_exp_f32_e32 v137, v89
	v_exp_f32_e32 v138, v90
	v_exp_f32_e32 v139, v91
	s_waitcnt lgkmcnt(4)
	v_mfma_f32_32x32x16_bf16 v[96:111], v[140:143], v[176:179], v[96:111]
	v_exp_f32_e32 v185, v92
	v_exp_f32_e32 v186, v93
	v_exp_f32_e32 v187, v94
	v_exp_f32_e32 v210, v95
	s_waitcnt lgkmcnt(3)
	v_mfma_f32_32x32x16_bf16 v[112:127], v[144:147], v[172:175], v[112:127]
	v_exp_f32_e32 v140, v64
	v_exp_f32_e32 v141, v65
	v_exp_f32_e32 v142, v66
	v_exp_f32_e32 v143, v67
	s_waitcnt lgkmcnt(1)
	v_mfma_f32_32x32x16_bf16 v[96:111], v[152:155], v[172:175], v[96:111]
	v_exp_f32_e32 v144, v68
	v_exp_f32_e32 v145, v69
	v_exp_f32_e32 v146, v70
	v_exp_f32_e32 v147, v71
	v_mfma_f32_32x32x16_bf16 v[112:127], v[148:151], v[168:171], v[112:127]
	v_exp_f32_e32 v152, v72
	v_exp_f32_e32 v153, v73
	v_exp_f32_e32 v154, v74
	v_exp_f32_e32 v155, v75
	s_waitcnt lgkmcnt(0)
	v_mfma_f32_32x32x16_bf16 v[96:111], v[156:159], v[168:171], v[96:111]
	v_exp_f32_e32 v148, v76
	v_exp_f32_e32 v149, v77
	v_exp_f32_e32 v150, v78
	v_exp_f32_e32 v151, v79
	s_cmp_gt_i32 s26, 2
	s_cselect_b32 s27, -3, 2
	s_add_i32 s27, s27, s26
	s_mulk_i32 s27, 0x2400
	s_waitcnt vmcnt(3)
	ds_write_b128 v208, v[6:9] offset:27648
	v_add_u32_e32 v6, s27, v208
	s_add_i32 s27, s26, 1
	s_cmp_lg_u32 s26, 4
	s_cselect_b32 s27, s27, 0
	s_add_i32 s26, s13, -3
	s_min_u32 s28, s26, s12
	s_lshl_b32 s92, s28, 13
	s_waitcnt vmcnt(2)
	ds_write_b128 v6, v[2:5] offset:36864
	s_add_u32 vcc_lo, s100, s92
	s_addc_u32 vcc_hi, s101, 0
	global_load_dwordx4 v[6:9], v248, vcc
	s_nop 0
	s_add_i32 s92, s13, -4
	s_lshl_b32 s92, s92, 7
	s_add_u32 vcc_lo, s98, s92
	s_addc_u32 vcc_hi, s99, 0
	global_load_dwordx4 v[2:5], v249, vcc
	s_mul_i32 s29, s27, 0x2400
	s_add_i32 s34, s29, 0xffffdc00
	s_cmp_lg_u32 s27, 0
	s_cselect_b32 s34, s34, 0x9000
	v_add_u32_e32 v14, s34, v195
	ds_read_b128 v[64:67], v14 offset:36864
	ds_read_b128 v[68:71], v14 offset:36896
	ds_read_b128 v[72:75], v14 offset:41472
	ds_read_b128 v[76:79], v14 offset:41504
	ds_read_b128 v[80:83], v14 offset:36928
	ds_read_b128 v[84:87], v14 offset:36960
	ds_read_b128 v[88:91], v14 offset:41536
	ds_read_b128 v[92:95], v14 offset:41568
	s_setprio 3
	v_cvt_pk_bf16_f32 v132, v161, v162
	v_cvt_pk_bf16_f32 v133, v163, v164
	v_cvt_pk_bf16_f32 v134, v165, v166
	v_cvt_pk_bf16_f32 v135, v167, v184
	s_waitcnt lgkmcnt(7)
	s_nop 0
	v_mfma_f32_32x32x16_bf16 v[16:31], v[64:67], v[132:135], v[16:31]
	v_add_f32_e32 v14, v161, v162
	v_add_f32_e32 v14, v14, v163
	v_add_f32_e32 v14, v14, v164
	s_waitcnt lgkmcnt(5)
	v_mfma_f32_32x32x16_bf16 v[32:47], v[72:75], v[132:135], v[32:47]
	v_cvt_pk_bf16_f32 v64, v136, v137
	v_cvt_pk_bf16_f32 v65, v138, v139
	v_cvt_pk_bf16_f32 v66, v185, v186
	v_cvt_pk_bf16_f32 v67, v187, v210
	v_add_f32_e32 v14, v14, v165
	v_add_f32_e32 v14, v14, v166
	v_add_f32_e32 v14, v14, v167
	v_add_f32_e32 v14, v14, v184
	s_nop 0
	v_mfma_f32_32x32x16_bf16 v[16:31], v[68:71], v[64:67], v[16:31]
	v_add_f32_e32 v14, v14, v136
	v_add_f32_e32 v14, v14, v137
	v_add_f32_e32 v14, v14, v138
	v_add_f32_e32 v14, v14, v139
	s_waitcnt lgkmcnt(4)
	v_mfma_f32_32x32x16_bf16 v[32:47], v[76:79], v[64:67], v[32:47]
	v_cvt_pk_bf16_f32 v68, v140, v141
	v_cvt_pk_bf16_f32 v69, v142, v143
	v_cvt_pk_bf16_f32 v70, v144, v145
	v_cvt_pk_bf16_f32 v71, v146, v147
	v_add_f32_e32 v14, v14, v185
	v_add_f32_e32 v14, v14, v186
	v_add_f32_e32 v14, v14, v187
	v_add_f32_e32 v14, v14, v210
	s_waitcnt lgkmcnt(3)
	v_mfma_f32_32x32x16_bf16 v[16:31], v[80:83], v[68:71], v[16:31]
	v_add_f32_e32 v14, v14, v140
	v_add_f32_e32 v14, v14, v141
	v_add_f32_e32 v14, v14, v142
	v_add_f32_e32 v14, v14, v143
	s_waitcnt lgkmcnt(1)
	v_mfma_f32_32x32x16_bf16 v[32:47], v[88:91], v[68:71], v[32:47]
	v_cvt_pk_bf16_f32 v64, v152, v153
	v_cvt_pk_bf16_f32 v65, v154, v155
	v_cvt_pk_bf16_f32 v66, v148, v149
	v_cvt_pk_bf16_f32 v67, v150, v151
	v_add_f32_e32 v14, v14, v144
	v_add_f32_e32 v14, v14, v145
	v_add_f32_e32 v14, v14, v146
	v_add_f32_e32 v14, v14, v147
	s_nop 0
	v_mfma_f32_32x32x16_bf16 v[16:31], v[84:87], v[64:67], v[16:31]
	v_add_f32_e32 v14, v14, v152
	v_add_f32_e32 v14, v14, v153
	v_add_f32_e32 v14, v14, v154
	v_add_f32_e32 v14, v14, v155
	s_waitcnt lgkmcnt(0)
	v_mfma_f32_32x32x16_bf16 v[32:47], v[92:95], v[64:67], v[32:47]
	v_add_f32_e32 v14, v14, v148
	v_add_f32_e32 v14, v14, v149
	v_add_f32_e32 v14, v14, v150
	v_add_f32_e32 v14, v14, v151
	s_setprio 2
	s_waitcnt lgkmcnt(0)
	s_barrier
	ds_read_b128 v[240:243], v195 offset:18432
	ds_read_b128 v[244:247], v195 offset:23040
	ds_read_b128 v[136:139], v195 offset:18464
	ds_read_b128 v[140:143], v195 offset:23072
	ds_read_b128 v[144:147], v195 offset:18496
	ds_read_b128 v[148:151], v195 offset:23104
	ds_read_b128 v[152:155], v195 offset:18528
	ds_read_b128 v[156:159], v195 offset:23136
	v_add_f32_e32 v1, v1, v160
	v_exp_f32_e32 v160, v112
	v_exp_f32_e32 v161, v113
	v_exp_f32_e32 v162, v114
	v_exp_f32_e32 v163, v115
	s_waitcnt lgkmcnt(6)
	v_mfma_f32_32x32x16_bf16 v[80:95], v[240:243], v[180:183], v[48:63]
	v_mfma_f32_32x32x16_bf16 v[64:79], v[244:247], v[180:183], v[48:63]
	v_exp_f32_e32 v164, v116
	v_exp_f32_e32 v165, v117
	v_exp_f32_e32 v166, v118
	v_exp_f32_e32 v167, v119
	s_waitcnt lgkmcnt(5)
	v_mfma_f32_32x32x16_bf16 v[80:95], v[136:139], v[176:179], v[80:95]
	v_exp_f32_e32 v184, v120
	v_exp_f32_e32 v185, v121
	v_exp_f32_e32 v186, v122
	v_exp_f32_e32 v187, v123
	s_waitcnt lgkmcnt(4)
	v_mfma_f32_32x32x16_bf16 v[64:79], v[140:143], v[176:179], v[64:79]
	v_exp_f32_e32 v136, v124
	v_exp_f32_e32 v137, v125
	v_exp_f32_e32 v138, v126
	v_exp_f32_e32 v139, v127
	s_waitcnt lgkmcnt(3)
	v_mfma_f32_32x32x16_bf16 v[80:95], v[144:147], v[172:175], v[80:95]
	v_exp_f32_e32 v140, v96
	v_exp_f32_e32 v141, v97
	v_exp_f32_e32 v142, v98
	v_exp_f32_e32 v143, v99
	s_waitcnt lgkmcnt(2)
	v_mfma_f32_32x32x16_bf16 v[64:79], v[148:151], v[172:175], v[64:79]
	v_exp_f32_e32 v144, v100
	v_exp_f32_e32 v145, v101
	v_exp_f32_e32 v146, v102
	v_exp_f32_e32 v147, v103
	s_waitcnt lgkmcnt(1)
	v_mfma_f32_32x32x16_bf16 v[80:95], v[152:155], v[168:171], v[80:95]
	v_exp_f32_e32 v148, v104
	v_exp_f32_e32 v149, v105
	v_exp_f32_e32 v150, v106
	v_exp_f32_e32 v151, v107
	s_waitcnt lgkmcnt(0)
	v_mfma_f32_32x32x16_bf16 v[64:79], v[156:159], v[168:171], v[64:79]
	v_exp_f32_e32 v152, v108
	v_exp_f32_e32 v153, v109
	v_exp_f32_e32 v154, v110
	v_exp_f32_e32 v155, v111
	s_cmp_gt_i32 s27, 2
	s_cselect_b32 s34, -3, 2
	s_waitcnt vmcnt(3)
	ds_write_b128 v208, v[128:131]
	v_add_u32_e32 v128, s29, v195
	ds_read_b128 v[240:243], v195 offset:27648
	ds_read_b128 v[244:247], v195 offset:32256
	ds_read_b128 v[96:99], v128 offset:41472
	ds_read_b128 v[100:103], v128 offset:36864
	ds_read_b128 v[104:107], v128 offset:36896
	ds_read_b128 v[108:111], v128 offset:41504
	ds_read_b128 v[116:119], v128 offset:36928
	ds_read_b128 v[120:123], v128 offset:41536
	ds_read_b128 v[124:127], v128 offset:36960
	ds_read_b128 v[128:131], v128 offset:41568
	s_add_i32 s34, s34, s27
	s_add_i32 s29, s13, -2
	s_mulk_i32 s34, 0x2400
	s_min_u32 s29, s29, s12
	v_add_u32_e32 v15, s34, v208
	s_lshl_b32 s92, s29, 13
	s_waitcnt vmcnt(2)
	ds_write_b128 v15, v[10:13] offset:36864
	s_add_u32 vcc_lo, s100, s92
	s_addc_u32 vcc_hi, s101, 0
	global_load_dwordx4 v[10:13], v248, vcc
	s_lshl_b32 s92, s28, 7
	v_add_f32_e32 v1, v1, v14
	s_add_u32 vcc_lo, s98, s92
	s_addc_u32 vcc_hi, s99, 0
	global_load_dwordx4 v[112:115], v249, vcc
	s_add_i32 s34, s27, 1
	s_setprio 1
	v_cvt_pk_bf16_f32 v132, v160, v161
	v_cvt_pk_bf16_f32 v133, v162, v163
	v_cvt_pk_bf16_f32 v134, v164, v165
	v_cvt_pk_bf16_f32 v135, v166, v167
	s_waitcnt lgkmcnt(7)
	s_nop 0
	v_mfma_f32_32x32x16_bf16 v[16:31], v[100:103], v[132:135], v[16:31]
	v_add_f32_e32 v14, v160, v161
	v_add_f32_e32 v14, v14, v162
	v_add_f32_e32 v14, v14, v163
	s_nop 0
	v_mfma_f32_32x32x16_bf16 v[32:47], v[96:99], v[132:135], v[32:47]
	v_cvt_pk_bf16_f32 v100, v184, v185
	v_cvt_pk_bf16_f32 v101, v186, v187
	v_cvt_pk_bf16_f32 v102, v136, v137
	v_cvt_pk_bf16_f32 v103, v138, v139
	v_add_f32_e32 v14, v14, v164
	v_add_f32_e32 v14, v14, v165
	v_add_f32_e32 v14, v14, v166
	v_add_f32_e32 v14, v14, v167
	s_waitcnt lgkmcnt(6)
	v_mfma_f32_32x32x16_bf16 v[16:31], v[104:107], v[100:103], v[16:31]
	v_add_f32_e32 v14, v14, v184
	v_add_f32_e32 v14, v14, v185
	v_add_f32_e32 v14, v14, v186
	v_add_f32_e32 v14, v14, v187
	s_waitcnt lgkmcnt(5)
	v_mfma_f32_32x32x16_bf16 v[32:47], v[108:111], v[100:103], v[32:47]
	v_cvt_pk_bf16_f32 v96, v140, v141
	v_cvt_pk_bf16_f32 v97, v142, v143
	v_cvt_pk_bf16_f32 v98, v144, v145
	v_cvt_pk_bf16_f32 v99, v146, v147
	v_add_f32_e32 v14, v14, v136
	v_add_f32_e32 v14, v14, v137
	v_add_f32_e32 v14, v14, v138
	v_add_f32_e32 v14, v14, v139
	s_waitcnt lgkmcnt(4)
	v_mfma_f32_32x32x16_bf16 v[16:31], v[116:119], v[96:99], v[16:31]
	v_add_f32_e32 v14, v14, v140
	v_add_f32_e32 v14, v14, v141
	v_add_f32_e32 v14, v14, v142
	v_add_f32_e32 v14, v14, v143
	s_waitcnt lgkmcnt(3)
	v_mfma_f32_32x32x16_bf16 v[32:47], v[120:123], v[96:99], v[32:47]
	v_cvt_pk_bf16_f32 v100, v148, v149
	v_cvt_pk_bf16_f32 v101, v150, v151
	v_cvt_pk_bf16_f32 v102, v152, v153
	v_cvt_pk_bf16_f32 v103, v154, v155
	v_add_f32_e32 v14, v14, v144
	v_add_f32_e32 v14, v14, v145
	v_add_f32_e32 v14, v14, v146
	v_add_f32_e32 v14, v14, v147
	s_waitcnt lgkmcnt(2)
	v_mfma_f32_32x32x16_bf16 v[16:31], v[124:127], v[100:103], v[16:31]
	v_add_f32_e32 v14, v14, v148
	v_add_f32_e32 v14, v14, v149
	v_add_f32_e32 v14, v14, v150
	v_add_f32_e32 v14, v14, v151
	s_waitcnt lgkmcnt(1)
	v_mfma_f32_32x32x16_bf16 v[32:47], v[128:131], v[100:103], v[32:47]
	v_add_f32_e32 v14, v14, v152
	v_add_f32_e32 v14, v14, v153
	v_add_f32_e32 v14, v14, v154
	v_add_f32_e32 v14, v14, v155
	s_setprio 0
	ds_read_b128 v[116:119], v195 offset:27680
	ds_read_b128 v[124:127], v195 offset:32288
	ds_read_b128 v[128:131], v195 offset:27712
	ds_read_b128 v[132:135], v195 offset:27744
	ds_read_b128 v[136:139], v195 offset:32320
	ds_read_b128 v[140:143], v195 offset:32352
	s_cmp_lg_u32 s27, 4
	s_cselect_b32 s27, s34, 0
	s_waitcnt lgkmcnt(6)
	v_mfma_f32_32x32x16_bf16 v[152:167], v[240:243], v[180:183], v[48:63]
	v_exp_f32_e32 v15, v80
	v_exp_f32_e32 v144, v81
	v_exp_f32_e32 v145, v82
	v_exp_f32_e32 v146, v83
	s_waitcnt lgkmcnt(5)
	v_mfma_f32_32x32x16_bf16 v[96:111], v[244:247], v[180:183], v[48:63]
	v_exp_f32_e32 v147, v84
	v_exp_f32_e32 v148, v85
	v_exp_f32_e32 v149, v86
	v_exp_f32_e32 v150, v87
	v_mfma_f32_32x32x16_bf16 v[152:167], v[116:119], v[176:179], v[152:167]
	v_exp_f32_e32 v120, v88
	v_exp_f32_e32 v121, v89
	v_exp_f32_e32 v122, v90
	v_exp_f32_e32 v123, v91
	s_waitcnt lgkmcnt(4)
	v_mfma_f32_32x32x16_bf16 v[96:111], v[124:127], v[176:179], v[96:111]
	v_exp_f32_e32 v151, v92
	v_exp_f32_e32 v184, v93
	v_exp_f32_e32 v185, v94
	v_exp_f32_e32 v186, v95
	s_waitcnt lgkmcnt(3)
	v_mfma_f32_32x32x16_bf16 v[152:167], v[128:131], v[172:175], v[152:167]
	v_exp_f32_e32 v124, v64
	v_exp_f32_e32 v125, v65
	v_exp_f32_e32 v126, v66
	v_exp_f32_e32 v127, v67
	s_waitcnt lgkmcnt(1)
	v_mfma_f32_32x32x16_bf16 v[96:111], v[136:139], v[172:175], v[96:111]
	v_exp_f32_e32 v128, v68
	v_exp_f32_e32 v129, v69
	v_exp_f32_e32 v130, v70
	v_exp_f32_e32 v131, v71
	v_mfma_f32_32x32x16_bf16 v[152:167], v[132:135], v[168:171], v[152:167]
	v_exp_f32_e32 v136, v72
	v_exp_f32_e32 v137, v73
	v_exp_f32_e32 v138, v74
	v_exp_f32_e32 v139, v75
	s_waitcnt lgkmcnt(0)
	v_mfma_f32_32x32x16_bf16 v[96:111], v[140:143], v[168:171], v[96:111]
	v_exp_f32_e32 v132, v76
	v_exp_f32_e32 v133, v77
	v_exp_f32_e32 v134, v78
	v_exp_f32_e32 v135, v79
	s_cmp_gt_i32 s27, 2
	s_cselect_b32 s28, -3, 2
	s_add_i32 s28, s28, s27
	s_mulk_i32 s28, 0x2400
	s_waitcnt vmcnt(3)
	ds_write_b128 v208, v[6:9] offset:9216
	v_add_u32_e32 v6, s28, v208
	s_add_i32 s28, s27, 1
	s_cmp_lg_u32 s27, 4
	s_cselect_b32 s27, s28, 0
	s_add_i32 s28, s13, -1
	s_min_u32 s28, s28, s12
	s_lshl_b32 s92, s28, 13
	s_waitcnt vmcnt(2)
	ds_write_b128 v6, v[2:5] offset:36864
	s_add_u32 vcc_lo, s100, s92
	s_addc_u32 vcc_hi, s101, 0
	global_load_dwordx4 v[6:9], v248, vcc
	s_lshl_b32 s92, s29, 7
	s_add_u32 vcc_lo, s98, s92
	s_addc_u32 vcc_hi, s99, 0
	global_load_dwordx4 v[2:5], v249, vcc
	s_nop 0
	s_mul_i32 s29, s27, 0x2400
	s_add_i32 s34, s29, 0xffffdc00
	s_cmp_lg_u32 s27, 0
	s_cselect_b32 s34, s34, 0x9000
	v_add_u32_e32 v92, s34, v195
	ds_read_b128 v[64:67], v92 offset:36864
	ds_read_b128 v[68:71], v92 offset:36896
	ds_read_b128 v[72:75], v92 offset:41472
	ds_read_b128 v[76:79], v92 offset:41504
	ds_read_b128 v[80:83], v92 offset:36928
	ds_read_b128 v[84:87], v92 offset:36960
	ds_read_b128 v[88:91], v92 offset:41536
	ds_read_b128 v[92:95], v92 offset:41568
	s_setprio 3
	v_cvt_pk_bf16_f32 v116, v15, v144
	v_cvt_pk_bf16_f32 v117, v145, v146
	v_cvt_pk_bf16_f32 v118, v147, v148
	v_cvt_pk_bf16_f32 v119, v149, v150
	v_add_f32_e32 v187, v15, v144
	v_add_f32_e32 v187, v187, v145
	v_add_f32_e32 v187, v187, v146
	v_add_f32_e32 v187, v187, v147
	v_add_f32_e32 v187, v187, v148
	v_add_f32_e32 v187, v187, v149
	v_add_f32_e32 v187, v187, v150
	s_waitcnt lgkmcnt(7)
	s_nop 0
	v_mfma_f32_32x32x16_bf16 v[16:31], v[64:67], v[116:119], v[16:31]
	s_waitcnt lgkmcnt(5)
	v_mfma_f32_32x32x16_bf16 v[32:47], v[72:75], v[116:119], v[32:47]
	v_cvt_pk_bf16_f32 v64, v120, v121
	v_cvt_pk_bf16_f32 v65, v122, v123
	v_cvt_pk_bf16_f32 v66, v151, v184
	v_cvt_pk_bf16_f32 v67, v185, v186
	s_nop 0
	v_mfma_f32_32x32x16_bf16 v[16:31], v[68:71], v[64:67], v[16:31]
	v_add_f32_e32 v187, v187, v120
	v_add_f32_e32 v187, v187, v121
	v_add_f32_e32 v187, v187, v122
	v_add_f32_e32 v187, v187, v123
	s_waitcnt lgkmcnt(4)
	v_mfma_f32_32x32x16_bf16 v[32:47], v[76:79], v[64:67], v[32:47]
	v_cvt_pk_bf16_f32 v68, v124, v125
	v_cvt_pk_bf16_f32 v69, v126, v127
	v_cvt_pk_bf16_f32 v70, v128, v129
	v_cvt_pk_bf16_f32 v71, v130, v131
	v_add_f32_e32 v187, v187, v151
	v_add_f32_e32 v187, v187, v184
	v_add_f32_e32 v187, v187, v185
	v_add_f32_e32 v187, v187, v186
	s_waitcnt lgkmcnt(3)
	v_mfma_f32_32x32x16_bf16 v[16:31], v[80:83], v[68:71], v[16:31]
	v_add_f32_e32 v187, v187, v124
	v_add_f32_e32 v187, v187, v125
	v_add_f32_e32 v187, v187, v126
	v_add_f32_e32 v187, v187, v127
	s_waitcnt lgkmcnt(1)
	v_mfma_f32_32x32x16_bf16 v[32:47], v[88:91], v[68:71], v[32:47]
	v_cvt_pk_bf16_f32 v64, v136, v137
	v_cvt_pk_bf16_f32 v65, v138, v139
	v_cvt_pk_bf16_f32 v66, v132, v133
	v_cvt_pk_bf16_f32 v67, v134, v135
	v_add_f32_e32 v187, v187, v128
	v_add_f32_e32 v187, v187, v129
	v_add_f32_e32 v187, v187, v130
	v_add_f32_e32 v187, v187, v131
	s_nop 0
	v_mfma_f32_32x32x16_bf16 v[16:31], v[84:87], v[64:67], v[16:31]
	v_add_f32_e32 v187, v187, v136
	v_add_f32_e32 v187, v187, v137
	v_add_f32_e32 v187, v187, v138
	v_add_f32_e32 v187, v187, v139
	s_waitcnt lgkmcnt(0)
	v_mfma_f32_32x32x16_bf16 v[32:47], v[92:95], v[64:67], v[32:47]
	v_add_f32_e32 v187, v187, v132
	v_add_f32_e32 v187, v187, v133
	v_add_f32_e32 v187, v187, v134
	v_add_f32_e32 v187, v187, v135
	s_setprio 2
	s_waitcnt lgkmcnt(0)
	s_barrier
	ds_read_b128 v[240:243], v195
	ds_read_b128 v[244:247], v195 offset:4608
	ds_read_b128 v[72:75], v195 offset:32
	ds_read_b128 v[76:79], v195 offset:4640
	ds_read_b128 v[80:83], v195 offset:64
	ds_read_b128 v[84:87], v195 offset:4672
	ds_read_b128 v[88:91], v195 offset:96
	ds_read_b128 v[92:95], v195 offset:4704
	v_add_f32_e32 v1, v1, v14
	v_exp_f32_e32 v14, v152
	v_exp_f32_e32 v15, v153
	v_exp_f32_e32 v116, v154
	v_exp_f32_e32 v117, v155
	s_waitcnt lgkmcnt(6)
	v_mfma_f32_32x32x16_bf16 v[136:151], v[240:243], v[180:183], v[48:63]
	v_mfma_f32_32x32x16_bf16 v[120:135], v[244:247], v[180:183], v[48:63]
	v_exp_f32_e32 v118, v156
	v_exp_f32_e32 v119, v157
	v_exp_f32_e32 v184, v158
	v_exp_f32_e32 v185, v159
	s_waitcnt lgkmcnt(5)
	v_mfma_f32_32x32x16_bf16 v[136:151], v[72:75], v[176:179], v[136:151]
	v_exp_f32_e32 v186, v160
	v_exp_f32_e32 v210, v161
	v_exp_f32_e32 v211, v162
	v_exp_f32_e32 v212, v163
	s_waitcnt lgkmcnt(4)
	v_mfma_f32_32x32x16_bf16 v[120:135], v[76:79], v[176:179], v[120:135]
	v_exp_f32_e32 v160, v164
	v_exp_f32_e32 v161, v165
	v_exp_f32_e32 v162, v166
	v_exp_f32_e32 v163, v167
	s_waitcnt lgkmcnt(3)
	v_mfma_f32_32x32x16_bf16 v[136:151], v[80:83], v[172:175], v[136:151]
	v_exp_f32_e32 v164, v96
	v_exp_f32_e32 v165, v97
	v_exp_f32_e32 v166, v98
	v_exp_f32_e32 v167, v99
	s_waitcnt lgkmcnt(2)
	v_mfma_f32_32x32x16_bf16 v[120:135], v[84:87], v[172:175], v[120:135]
	v_exp_f32_e32 v96, v100
	v_exp_f32_e32 v97, v101
	v_exp_f32_e32 v98, v102
	v_exp_f32_e32 v99, v103
	s_waitcnt lgkmcnt(1)
	v_mfma_f32_32x32x16_bf16 v[136:151], v[88:91], v[168:171], v[136:151]
	v_exp_f32_e32 v100, v104
	v_exp_f32_e32 v101, v105
	v_exp_f32_e32 v102, v106
	v_exp_f32_e32 v103, v107
	s_waitcnt lgkmcnt(0)
	v_mfma_f32_32x32x16_bf16 v[120:135], v[92:95], v[168:171], v[120:135]
	v_exp_f32_e32 v104, v108
	v_exp_f32_e32 v105, v109
	v_exp_f32_e32 v106, v110
	v_exp_f32_e32 v107, v111
	s_cmp_gt_i32 s27, 2
	s_cselect_b32 s34, -3, 2
	s_add_i32 s34, s34, s27
	s_mulk_i32 s34, 0x2400
	v_add_u32_e32 v88, s29, v195
	s_min_u32 s29, s13, s12
	s_waitcnt vmcnt(3)
	ds_write_b128 v208, v[10:13] offset:18432
	v_add_u32_e32 v10, s34, v208
	s_lshl_b32 s92, s29, 13
	s_waitcnt vmcnt(2)
	ds_write_b128 v10, v[112:115] offset:36864
	ds_read_b128 v[240:243], v195 offset:9216
	ds_read_b128 v[244:247], v195 offset:13824
	ds_read_b128 v[10:13], v88 offset:41472
	ds_read_b128 v[64:67], v88 offset:36864
	ds_read_b128 v[68:71], v88 offset:36896
	ds_read_b128 v[72:75], v88 offset:41504
	ds_read_b128 v[76:79], v88 offset:36928
	ds_read_b128 v[80:83], v88 offset:41536
	ds_read_b128 v[84:87], v88 offset:36960
	ds_read_b128 v[88:91], v88 offset:41568
	s_add_u32 vcc_lo, s100, s92
	s_addc_u32 vcc_hi, s101, 0
	global_load_dwordx4 v[152:155], v248, vcc
	s_lshl_b32 s92, s28, 7
	s_add_u32 vcc_lo, s98, s92
	s_addc_u32 vcc_hi, s99, 0
	global_load_dwordx4 v[156:159], v249, vcc
	v_add_f32_e32 v1, v1, v187
	s_setprio 1
	v_mov_b32_e32 v109, v136
	v_cvt_pk_bf16_f32 v92, v14, v15
	v_cvt_pk_bf16_f32 v93, v116, v117
	v_cvt_pk_bf16_f32 v94, v118, v119
	v_cvt_pk_bf16_f32 v95, v184, v185
	s_waitcnt lgkmcnt(6)
	s_nop 0
	v_mfma_f32_32x32x16_bf16 v[16:31], v[64:67], v[92:95], v[16:31]
	v_max3_f32 v109, v109, v137, v138
	v_max3_f32 v109, v109, v139, v140
	v_add_f32_e32 v108, v14, v15
	v_add_f32_e32 v108, v108, v116
	v_add_f32_e32 v108, v108, v117
	s_nop 0
	v_mfma_f32_32x32x16_bf16 v[32:47], v[10:13], v[92:95], v[32:47]
	v_cvt_pk_bf16_f32 v64, v186, v210
	v_cvt_pk_bf16_f32 v65, v211, v212
	v_cvt_pk_bf16_f32 v66, v160, v161
	v_cvt_pk_bf16_f32 v67, v162, v163
	v_max3_f32 v109, v109, v141, v142
	v_max3_f32 v109, v109, v143, v144
	v_add_f32_e32 v108, v108, v118
	v_add_f32_e32 v108, v108, v119
	v_add_f32_e32 v108, v108, v184
	v_add_f32_e32 v108, v108, v185
	s_waitcnt lgkmcnt(5)
	v_mfma_f32_32x32x16_bf16 v[16:31], v[68:71], v[64:67], v[16:31]
	v_max3_f32 v109, v109, v145, v146
	v_max3_f32 v109, v109, v147, v148
	v_add_f32_e32 v108, v108, v186
	v_add_f32_e32 v108, v108, v210
	v_add_f32_e32 v108, v108, v211
	v_add_f32_e32 v108, v108, v212
	s_waitcnt lgkmcnt(4)
	v_mfma_f32_32x32x16_bf16 v[32:47], v[72:75], v[64:67], v[32:47]
	v_cvt_pk_bf16_f32 v10, v164, v165
	v_cvt_pk_bf16_f32 v11, v166, v167
	v_cvt_pk_bf16_f32 v12, v96, v97
	v_cvt_pk_bf16_f32 v13, v98, v99
	v_max3_f32 v109, v109, v149, v150
	v_max3_f32 v109, v109, v151, v120
	v_add_f32_e32 v108, v108, v160
	v_add_f32_e32 v108, v108, v161
	v_add_f32_e32 v108, v108, v162
	v_add_f32_e32 v108, v108, v163
	s_waitcnt lgkmcnt(3)
	v_mfma_f32_32x32x16_bf16 v[16:31], v[76:79], v[10:13], v[16:31]
	v_max3_f32 v109, v109, v121, v122
	v_max3_f32 v109, v109, v123, v124
	v_add_f32_e32 v108, v108, v164
	v_add_f32_e32 v108, v108, v165
	v_add_f32_e32 v108, v108, v166
	v_add_f32_e32 v108, v108, v167
	s_waitcnt lgkmcnt(2)
	v_mfma_f32_32x32x16_bf16 v[32:47], v[80:83], v[10:13], v[32:47]
	v_cvt_pk_bf16_f32 v64, v100, v101
	v_cvt_pk_bf16_f32 v65, v102, v103
	v_cvt_pk_bf16_f32 v66, v104, v105
	v_cvt_pk_bf16_f32 v67, v106, v107
	v_max3_f32 v109, v109, v125, v126
	v_max3_f32 v109, v109, v127, v128
	v_add_f32_e32 v108, v108, v96
	v_add_f32_e32 v108, v108, v97
	v_add_f32_e32 v108, v108, v98
	v_add_f32_e32 v108, v108, v99
	s_waitcnt lgkmcnt(1)
	v_mfma_f32_32x32x16_bf16 v[16:31], v[84:87], v[64:67], v[16:31]
	v_max3_f32 v109, v109, v129, v130
	v_max3_f32 v109, v109, v131, v132
	v_add_f32_e32 v108, v108, v100
	v_add_f32_e32 v108, v108, v101
	v_add_f32_e32 v108, v108, v102
	v_add_f32_e32 v108, v108, v103
	s_waitcnt lgkmcnt(0)
	v_mfma_f32_32x32x16_bf16 v[32:47], v[88:91], v[64:67], v[32:47]
	v_max3_f32 v109, v109, v133, v134
	v_max3_f32 v109, v109, v135, v135
	v_add_f32_e32 v108, v108, v104
	v_add_f32_e32 v108, v108, v105
	v_add_f32_e32 v108, v108, v106
	v_add_f32_e32 v108, v108, v107
	s_setprio 0
	ds_read_b128 v[164:167], v195 offset:9248
	ds_read_b128 v[160:163], v195 offset:13856
	ds_read_b128 v[74:77], v195 offset:9280
	ds_read_b128 v[66:69], v195 offset:9312
	ds_read_b128 v[70:73], v195 offset:13888
	ds_read_b128 v[10:13], v195 offset:13920
	v_add_f32_e32 v64, v1, v108
	v_mov_b32_e32 v1, v109
	s_nop 1
	v_permlane32_swap_b32_e32 v109, v1
	v_max_f32_e32 v1, v1, v1
	v_max_f32_e32 v14, v109, v109
	v_max_f32_e32 v1, v14, v1
	v_cmp_lt_f32_e32 vcc, s52, v1
	s_cbranch_vccz .LBB0_663
	v_max_f32_e32 v1, v1, v1
	v_max_f32_e32 v14, 0, v1
	v_add_f32_e32 v209, v209, v14
	v_xor_b32_e32 v48, 0x80000000, v209
	v_pk_add_f32 v[136:137], v[136:137], v[14:15] op_sel_hi:[1,0] neg_lo:[0,1] neg_hi:[0,1]
	v_pk_add_f32 v[120:121], v[120:121], v[14:15] op_sel_hi:[1,0] neg_lo:[0,1] neg_hi:[0,1]
	v_pk_add_f32 v[138:139], v[138:139], v[14:15] op_sel_hi:[1,0] neg_lo:[0,1] neg_hi:[0,1]
	v_pk_add_f32 v[122:123], v[122:123], v[14:15] op_sel_hi:[1,0] neg_lo:[0,1] neg_hi:[0,1]
	v_pk_add_f32 v[140:141], v[140:141], v[14:15] op_sel_hi:[1,0] neg_lo:[0,1] neg_hi:[0,1]
	v_pk_add_f32 v[124:125], v[124:125], v[14:15] op_sel_hi:[1,0] neg_lo:[0,1] neg_hi:[0,1]
	v_pk_add_f32 v[142:143], v[142:143], v[14:15] op_sel_hi:[1,0] neg_lo:[0,1] neg_hi:[0,1]
	v_pk_add_f32 v[126:127], v[126:127], v[14:15] op_sel_hi:[1,0] neg_lo:[0,1] neg_hi:[0,1]
	v_pk_add_f32 v[144:145], v[144:145], v[14:15] op_sel_hi:[1,0] neg_lo:[0,1] neg_hi:[0,1]
	v_pk_add_f32 v[128:129], v[128:129], v[14:15] op_sel_hi:[1,0] neg_lo:[0,1] neg_hi:[0,1]
	v_pk_add_f32 v[146:147], v[146:147], v[14:15] op_sel_hi:[1,0] neg_lo:[0,1] neg_hi:[0,1]
	v_pk_add_f32 v[130:131], v[130:131], v[14:15] op_sel_hi:[1,0] neg_lo:[0,1] neg_hi:[0,1]
	v_pk_add_f32 v[148:149], v[148:149], v[14:15] op_sel_hi:[1,0] neg_lo:[0,1] neg_hi:[0,1]
	v_pk_add_f32 v[132:133], v[132:133], v[14:15] op_sel_hi:[1,0] neg_lo:[0,1] neg_hi:[0,1]
	v_pk_add_f32 v[150:151], v[150:151], v[14:15] op_sel_hi:[1,0] neg_lo:[0,1] neg_hi:[0,1]
	v_pk_add_f32 v[134:135], v[134:135], v[14:15] op_sel_hi:[1,0] neg_lo:[0,1] neg_hi:[0,1]
	v_exp_f32_e64 v14, -v14
	v_mov_b32_e32 v49, v48
	v_mov_b32_e32 v50, v48
	v_mov_b32_e32 v51, v48
	v_mov_b32_e32 v52, v48
	v_mov_b32_e32 v53, v48
	v_mov_b32_e32 v54, v48
	v_mov_b32_e32 v55, v48
	v_mov_b32_e32 v56, v48
	v_mov_b32_e32 v57, v48
	v_mov_b32_e32 v58, v48
	v_mov_b32_e32 v59, v48
	v_mov_b32_e32 v60, v48
	v_mov_b32_e32 v61, v48
	v_mov_b32_e32 v62, v48
	v_mov_b32_e32 v63, v48
	s_nop 11
	v_pk_mul_f32 v[30:31], v[30:31], v[14:15] op_sel_hi:[1,0]
	v_pk_mul_f32 v[28:29], v[28:29], v[14:15] op_sel_hi:[1,0]
	v_pk_mul_f32 v[26:27], v[26:27], v[14:15] op_sel_hi:[1,0]
	v_pk_mul_f32 v[24:25], v[24:25], v[14:15] op_sel_hi:[1,0]
	v_pk_mul_f32 v[22:23], v[22:23], v[14:15] op_sel_hi:[1,0]
	v_pk_mul_f32 v[20:21], v[20:21], v[14:15] op_sel_hi:[1,0]
	v_pk_mul_f32 v[18:19], v[18:19], v[14:15] op_sel_hi:[1,0]
	v_pk_mul_f32 v[16:17], v[16:17], v[14:15] op_sel_hi:[1,0]
	v_pk_mul_f32 v[46:47], v[46:47], v[14:15] op_sel_hi:[1,0]
	v_pk_mul_f32 v[44:45], v[44:45], v[14:15] op_sel_hi:[1,0]
	v_pk_mul_f32 v[42:43], v[42:43], v[14:15] op_sel_hi:[1,0]
	v_pk_mul_f32 v[40:41], v[40:41], v[14:15] op_sel_hi:[1,0]
	v_pk_mul_f32 v[38:39], v[38:39], v[14:15] op_sel_hi:[1,0]
	v_pk_mul_f32 v[36:37], v[36:37], v[14:15] op_sel_hi:[1,0]
	v_pk_mul_f32 v[34:35], v[34:35], v[14:15] op_sel_hi:[1,0]
	v_pk_mul_f32 v[32:33], v[32:33], v[14:15] op_sel_hi:[1,0]
	v_mul_f32_e32 v64, v64, v14
